# prep phase GLA units: q,k and q~,k~,kd moved with 16-byte global accesses staged through LDS instead of 2-byte per-lane accesses
# speedup vs baseline: 1.0114x; 1.0114x over previous
.LBB0_459:
	s_add_i32 s89, s3, s48
	s_load_dwordx2 s[90:91], s[0:1], 0x100
	s_load_dwordx2 s[92:93], s[0:1], 0xf8
	s_and_b32 s98, s89, 3
	s_lshl_b32 s99, s98, 8
	s_bfe_u32 s98, s89, 0x60002
	s_lshl_b32 s98, s98, 6
	s_ashr_i32 s100, s89, 8
	s_lshl_b32 s100, s100, 12
	s_or_b32 s98, s98, s100
	v_lshrrev_b32_e32 v180, 5, v192
	v_and_b32_e32 v181, 15, v192
	v_lshlrev_b32_e32 v181, 4, v181
	v_bfe_u32 v182, v192, 4, 1
	v_lshl_add_u32 v181, v182, 10, v181
	v_mov_b32_e32 v183, 0
	v_and_b32_e32 v176, 31, v192
	v_lshlrev_b32_e32 v176, 4, v176
	v_lshl_add_u32 v176, v180, 9, v176
	v_add_u32_e32 v176, 0x10000, v176
	v_lshrrev_b32_e32 v177, 7, v192
	v_and_b32_e32 v178, 0x7f, v192
	v_lshlrev_b32_e32 v178, 1, v178
	v_lshl_add_u32 v179, v177, 13, v178
	v_add_u32_e32 v179, 0x10000, v179
	v_mul_u32_u24_e32 v177, 0x3000, v177
	v_add_u32_e32 v178, v177, v178
	v_add_u32_e32 v178, 0x18000, v178
	v_lshlrev_b32_e32 v177, 4, v192
	v_add_u32_e32 v177, 0x18000, v177
	s_waitcnt lgkmcnt(0)
	s_mul_i32 s100, s98, 0x2c00
	s_add_u32 s94, s90, s100
	s_addc_u32 s95, s91, 0
	s_add_u32 s94, s94, s99
	s_addc_u32 s95, s95, 0
	s_lshl_b32 s100, s98, 10
	s_add_u32 s96, s92, s100
	s_addc_u32 s97, s93, 0
	s_add_u32 s96, s96, s99
	s_addc_u32 s97, s97, 0
	s_movk_i32 s99, 0x2c00
	v_mov_b64_e32 v[184:185], s[94:95]
	v_mad_u64_u32 v[184:185], s[100:101], v180, s99, v[184:185]
	v_mov_b32_e32 v182, v181
	v_lshl_add_u64 v[184:185], v[184:185], 0, v[182:183]
	v_mov_b32_e32 v186, 0x2c000
	v_mov_b32_e32 v187, 0
	global_load_dwordx4 v[160:163], v[184:185], off
	v_lshl_add_u64 v[184:185], v[184:185], 0, v[186:187]
	global_load_dwordx4 v[164:167], v[184:185], off
	v_lshl_add_u64 v[184:185], v[184:185], 0, v[186:187]
	global_load_dwordx4 v[168:171], v[184:185], off
	v_lshl_add_u64 v[184:185], v[184:185], 0, v[186:187]
	global_load_dwordx4 v[172:175], v[184:185], off
	s_mov_b64 s[16:17], s[0:1]
	s_load_dwordx2 s[30:31], s[16:17], 0x100
	s_mov_b64 s[26:27], s[0:1]
	s_mov_b64 s[16:17], s[0:1]
	s_load_dwordx2 s[28:29], s[16:17], 0xf8
	s_mov_b64 s[16:17], s[0:1]
	s_mov_b64 s[50:51], s[0:1]
	s_load_dwordx2 s[52:53], s[50:51], 0x38
	s_and_b32 s49, s34, 0x180
	v_or_b32_e32 v2, s49, v0
	v_lshlrev_b32_e32 v2, 2, v2
	s_add_i32 s24, s3, s48
	s_waitcnt lgkmcnt(0)
	v_lshl_add_u64 v[12:13], s[52:53], 0, v[2:3]
	v_add_co_u32_e32 v14, vcc, s35, v12
	s_bfe_u32 s50, s24, 0x60002
	s_nop 0
	v_addc_co_u32_e32 v15, vcc, 0, v13, vcc
	v_add_co_u32_e32 v16, vcc, s36, v12
	s_ashr_i32 s51, s24, 8
	s_nop 0
	v_addc_co_u32_e32 v17, vcc, 0, v13, vcc
	v_add_co_u32_e32 v18, vcc, s37, v12
	s_lshl_b32 s24, s51, 12
	s_nop 0
	v_addc_co_u32_e32 v19, vcc, 0, v13, vcc
	v_add_co_u32_e32 v20, vcc, s38, v12
	s_nop 1
	v_addc_co_u32_e32 v21, vcc, 0, v13, vcc
	v_add_co_u32_e32 v22, vcc, s39, v12
	s_nop 1
	v_addc_co_u32_e32 v23, vcc, 0, v13, vcc
	v_add_co_u32_e32 v24, vcc, s40, v12
	s_nop 1
	v_addc_co_u32_e32 v25, vcc, 0, v13, vcc
	v_add_co_u32_e32 v12, vcc, s41, v12
	global_load_dword v106, v[16:17], off
	global_load_dword v107, v[16:17], off offset:2048
	global_load_dword v104, v[20:21], off offset:-4096
	global_load_dword v5, v[20:21], off
	global_load_dword v77, v[20:21], off offset:2048
	global_load_dword v99, v[24:25], off offset:-4096
	global_load_dword v76, v[24:25], off
	global_load_dword v100, v[24:25], off offset:2048
	v_addc_co_u32_e32 v13, vcc, 0, v13, vcc
	global_load_dword v110, v2, s[52:53]
	global_load_dword v113, v2, s[52:53] offset:2048
	global_load_dword v111, v[16:17], off offset:-4096
	global_load_dword v112, v[14:15], off offset:2048
	global_load_dword v109, v[18:19], off offset:2048
	global_load_dword v105, v[22:23], off offset:2048
	global_load_dword v102, v[12:13], off
	global_load_dword v101, v[12:13], off offset:2048
	s_mov_b64 s[52:53], s[0:1]
	s_load_dwordx2 s[54:55], s[52:53], 0x40
	s_lshl_b32 s52, s50, 6
	s_or_b32 s52, s52, s24
	v_add_u32_e32 v72, s52, v1
	v_mov_b64_e32 v[14:15], s[30:31]
	v_mad_i64_i32 v[12:13], s[30:31], v72, s42, v[14:15]
	s_lshl_b32 s24, s49, 1
	v_lshl_add_u64 v[12:13], v[12:13], 0, s[24:25]
	v_or_b32_e32 v68, 1, v72
	v_lshl_add_u64 v[74:75], v[12:13], 0, v[6:7]
	v_mad_i64_i32 v[12:13], s[30:31], v68, s42, v[14:15]
	v_lshl_add_u64 v[12:13], v[12:13], 0, s[24:25]
	v_or_b32_e32 v64, 2, v72
	v_lshl_add_u64 v[70:71], v[12:13], 0, v[6:7]
	v_mad_i64_i32 v[12:13], s[30:31], v64, s42, v[14:15]
	v_lshl_add_u64 v[12:13], v[12:13], 0, s[24:25]
	v_or_b32_e32 v60, 3, v72
	v_lshl_add_u64 v[66:67], v[12:13], 0, v[6:7]
	v_mad_i64_i32 v[12:13], s[30:31], v60, s42, v[14:15]
	v_lshl_add_u64 v[12:13], v[12:13], 0, s[24:25]
	v_or_b32_e32 v56, 4, v72
	v_lshl_add_u64 v[62:63], v[12:13], 0, v[6:7]
	v_mad_i64_i32 v[12:13], s[30:31], v56, s42, v[14:15]
	v_lshl_add_u64 v[12:13], v[12:13], 0, s[24:25]
	v_or_b32_e32 v52, 5, v72
	v_lshl_add_u64 v[58:59], v[12:13], 0, v[6:7]
	v_mad_i64_i32 v[12:13], s[30:31], v52, s42, v[14:15]
	v_lshl_add_u64 v[12:13], v[12:13], 0, s[24:25]
	v_or_b32_e32 v48, 6, v72
	v_lshl_add_u64 v[54:55], v[12:13], 0, v[6:7]
	v_mad_i64_i32 v[12:13], s[30:31], v48, s42, v[14:15]
	v_lshl_add_u64 v[12:13], v[12:13], 0, s[24:25]
	v_or_b32_e32 v44, 7, v72
	v_lshl_add_u64 v[50:51], v[12:13], 0, v[6:7]
	v_mad_i64_i32 v[12:13], s[30:31], v44, s42, v[14:15]
	v_lshl_add_u64 v[12:13], v[12:13], 0, s[24:25]
	v_or_b32_e32 v40, 8, v72
	v_lshl_add_u64 v[46:47], v[12:13], 0, v[6:7]
	v_mad_i64_i32 v[12:13], s[30:31], v40, s42, v[14:15]
	v_lshl_add_u64 v[12:13], v[12:13], 0, s[24:25]
	v_or_b32_e32 v36, 9, v72
	v_lshl_add_u64 v[42:43], v[12:13], 0, v[6:7]
	v_mad_i64_i32 v[12:13], s[30:31], v36, s42, v[14:15]
	v_lshl_add_u64 v[12:13], v[12:13], 0, s[24:25]
	v_or_b32_e32 v32, 10, v72
	v_lshl_add_u64 v[38:39], v[12:13], 0, v[6:7]
	v_mad_i64_i32 v[12:13], s[30:31], v32, s42, v[14:15]
	v_lshl_add_u64 v[12:13], v[12:13], 0, s[24:25]
	v_or_b32_e32 v28, 11, v72
	v_lshl_add_u64 v[34:35], v[12:13], 0, v[6:7]
	v_mad_i64_i32 v[12:13], s[30:31], v28, s42, v[14:15]
	v_lshl_add_u64 v[12:13], v[12:13], 0, s[24:25]
	v_or_b32_e32 v24, 12, v72
	v_lshl_add_u64 v[30:31], v[12:13], 0, v[6:7]
	v_mad_i64_i32 v[12:13], s[30:31], v24, s42, v[14:15]
	v_lshl_add_u64 v[12:13], v[12:13], 0, s[24:25]
	v_or_b32_e32 v20, 13, v72
	v_lshl_add_u64 v[26:27], v[12:13], 0, v[6:7]
	v_mad_i64_i32 v[12:13], s[30:31], v20, s42, v[14:15]
	v_lshl_add_u64 v[12:13], v[12:13], 0, s[24:25]
	v_or_b32_e32 v16, 14, v72
	v_lshl_add_u64 v[22:23], v[12:13], 0, v[6:7]
	v_mad_i64_i32 v[12:13], s[30:31], v16, s42, v[14:15]
	v_lshl_add_u64 v[12:13], v[12:13], 0, s[24:25]
	v_lshl_add_u64 v[18:19], v[12:13], 0, v[6:7]
	v_or_b32_e32 v12, 15, v72
	v_mad_i64_i32 v[14:15], s[30:31], v12, s42, v[14:15]
	v_lshl_add_u64 v[14:15], v[14:15], 0, s[24:25]
	s_waitcnt lgkmcnt(0)
	global_load_dword v117, v2, s[54:55]
	v_lshl_add_u64 v[14:15], v[14:15], 0, v[6:7]
	s_and_saveexec_b64 s[30:31], s[6:7]
	s_cbranch_execz .LBB0_461
	s_load_dwordx2 s[26:27], s[26:27], 0x100
	v_or_b32_e32 v126, s52, v78
	v_ashrrev_i32_e32 v127, 31, v126
	v_lshlrev_b64 v[126:127], 7, v[126:127]
	v_mov_b32_e32 v9, v3
	s_waitcnt lgkmcnt(0)
	v_lshl_add_u64 v[126:127], s[26:27], 0, v[126:127]
	v_lshl_add_u64 v[126:127], v[126:127], 0, v[8:9]
	v_add_co_u32_e32 v126, vcc, 0x1a200000, v126
	s_nop 1
	v_addc_co_u32_e32 v127, vcc, 0, v127, vcc
	global_load_dwordx4 v[134:137], v[126:127], off
	s_waitcnt vmcnt(0)
	ds_write_b128 v80, v[134:137]
.LBB0_461:
	s_or_b64 exec, exec, s[30:31]
	s_load_dwordx2 s[26:27], s[16:17], 0xf8
	s_waitcnt vmcnt(0)
	s_waitcnt vmcnt(0)
	ds_write_b128 v176, v[160:163]
	ds_write_b128 v176, v[164:167] offset:8192
	ds_write_b128 v176, v[168:171] offset:16384
	ds_write_b128 v176, v[172:175] offset:24576
	s_waitcnt lgkmcnt(0)
	s_barrier
	ds_read_u16 v98, v179
	ds_read_u16 v108, v179 offset:256
	ds_read_u16 v97, v179 offset:512
	ds_read_u16 v114, v179 offset:768
	ds_read_u16 v96, v179 offset:1024
	ds_read_u16 v116, v179 offset:1280
	ds_read_u16 v94, v179 offset:1536
	ds_read_u16 v118, v179 offset:1792
	ds_read_u16 v95, v179 offset:2048
	ds_read_u16 v119, v179 offset:2304
	ds_read_u16 v93, v179 offset:2560
	ds_read_u16 v132, v179 offset:2816
	ds_read_u16 v92, v179 offset:3072
	ds_read_u16 v131, v179 offset:3328
	ds_read_u16 v90, v179 offset:3584
	ds_read_u16 v103, v179 offset:3840
	ds_read_u16 v91, v179 offset:4096
	ds_read_u16 v115, v179 offset:4352
	ds_read_u16 v89, v179 offset:4608
	ds_read_u16 v130, v179 offset:4864
	ds_read_u16 v88, v179 offset:5120
	ds_read_u16 v128, v179 offset:5376
	ds_read_u16 v86, v179 offset:5632
	ds_read_u16 v129, v179 offset:5888
	ds_read_u16 v87, v179 offset:6144
	ds_read_u16 v121, v179 offset:6400
	ds_read_u16 v85, v179 offset:6656
	ds_read_u16 v122, v179 offset:6912
	ds_read_u16 v11, v179 offset:7168
	ds_read_u16 v123, v179 offset:7424
	ds_read_u16 v2, v179 offset:7680
	ds_read_u16 v125, v179 offset:7936
	s_waitcnt lgkmcnt(0)
	v_lshlrev_b32_e32 v124, 16, v116
	v_lshlrev_b32_e32 v116, 16, v132
	ds_read_b128 v[132:135], v81
	ds_read_b128 v[136:139], v81 offset:16
	ds_read_b128 v[140:143], v81 offset:32
	ds_read_b128 v[144:147], v81 offset:48
	v_lshlrev_b32_e32 v127, 16, v108
	v_lshlrev_b32_e32 v126, 16, v114
	s_waitcnt lgkmcnt(2)
	v_mul_f32_e32 v108, v107, v137
	v_mul_f32_e32 v9, v113, v133
	v_fmac_f32_e32 v9, v110, v132
	v_fmac_f32_e32 v9, v111, v134
	v_fmac_f32_e32 v108, v106, v136
	v_fmac_f32_e32 v9, v112, v135
	v_fmac_f32_e32 v108, v104, v138
	v_add_f32_e32 v9, v117, v9
	v_fmac_f32_e32 v108, v109, v139
	v_add_f32_e32 v9, v9, v108
	s_waitcnt lgkmcnt(1)
	v_mul_f32_e32 v108, v77, v141
	v_fmac_f32_e32 v108, v5, v140
	v_fmac_f32_e32 v108, v99, v142
	v_fmac_f32_e32 v108, v105, v143
	v_add_f32_e32 v9, v9, v108
	s_waitcnt lgkmcnt(0)
	v_mul_f32_e32 v108, v100, v145
	v_fmac_f32_e32 v108, v76, v144
	v_fmac_f32_e32 v108, v102, v146
	v_fmac_f32_e32 v108, v101, v147
	v_lshlrev_b32_e32 v114, 16, v131
	v_add_f32_e32 v131, v9, v108
	v_mul_f32_e64 v9, |v131|, s43
	v_exp_f32_e32 v9, v9
	v_lshlrev_b32_e32 v120, 16, v118
	v_lshlrev_b32_e32 v118, 16, v103
	v_lshlrev_b32_e32 v108, 16, v130
	v_add_f32_e32 v9, 1.0, v9
	v_cmp_gt_f32_e32 vcc, s44, v9
	v_min_f32_e32 v137, 0, v131
	v_ashrrev_i32_e32 v73, 31, v72
	v_cndmask_b32_e64 v103, 0, 32, vcc
	v_ldexp_f32 v9, v9, v103
	v_log_f32_e32 v136, v9
	v_lshlrev_b32_e32 v103, 16, v128
	v_lshlrev_b32_e32 v9, 16, v129
	ds_read_b128 v[128:131], v81 offset:64
	v_mul_f32_e32 v132, 0x3f317217, v136
	v_fma_f32 v138, v136, s45, -v132
	ds_read_b128 v[132:135], v81 offset:80
	v_fmac_f32_e32 v138, 0x3377d1cf, v136
	s_waitcnt lgkmcnt(1)
	v_mul_f32_e32 v129, v113, v129
	v_fmac_f32_e32 v129, v110, v128
	v_fmac_f32_e32 v129, v111, v130
	v_fmac_f32_e32 v129, v112, v131
	v_add_f32_e32 v139, v117, v129
	s_waitcnt lgkmcnt(0)
	v_mul_f32_e32 v133, v107, v133
	ds_read_b128 v[128:131], v81 offset:96
	v_fmac_f32_e32 v133, v106, v132
	v_fmac_f32_e32 v133, v104, v134
	v_fmac_f32_e32 v133, v109, v135
	v_add_f32_e32 v139, v139, v133
	ds_read_b128 v[132:135], v81 offset:112
	s_waitcnt lgkmcnt(1)
	v_mul_f32_e32 v129, v77, v129
	v_fmac_f32_e32 v129, v5, v128
	v_fmac_f32_e32 v129, v99, v130
	v_fmac_f32_e32 v129, v105, v131
	v_add_f32_e32 v128, v139, v129
	s_waitcnt lgkmcnt(0)
	v_mul_f32_e32 v129, v100, v133
	v_fmac_f32_e32 v129, v76, v132
	v_fmac_f32_e32 v129, v102, v134
	v_fmac_f32_e32 v129, v101, v135
	v_add_f32_e32 v129, v128, v129
	v_mul_f32_e64 v128, |v129|, s43
	v_exp_f32_e32 v128, v128
	v_fmac_f32_e32 v138, 0x3f317217, v136
	v_cmp_lt_f32_e64 s[16:17], |v136|, s46
	v_cndmask_b32_e32 v131, 0, v84, vcc
	v_add_f32_e32 v128, 1.0, v128
	v_cndmask_b32_e64 v130, v136, v138, s[16:17]
	v_cmp_gt_f32_e32 vcc, s44, v128
	v_sub_f32_e32 v130, v130, v131
	v_min_f32_e32 v129, 0, v129
	v_cndmask_b32_e64 v131, 0, 32, vcc
	v_ldexp_f32 v128, v128, v131
	v_log_f32_e32 v138, v128
	v_sub_f32_e32 v128, v137, v130
	ds_read_b128 v[130:133], v81 offset:128
	v_fma_f32 v128, v128, s47, 0
	v_mul_f32_e32 v134, 0x3f317217, v138
	v_fma_f32 v139, v138, s45, -v134
	ds_read_b128 v[134:137], v81 offset:144
	s_waitcnt lgkmcnt(1)
	v_mul_f32_e32 v131, v113, v131
	v_fmac_f32_e32 v131, v110, v130
	v_fmac_f32_e32 v131, v111, v132
	v_fmac_f32_e32 v131, v112, v133
	v_add_f32_e32 v140, v117, v131
	s_waitcnt lgkmcnt(0)
	v_mul_f32_e32 v135, v107, v135
	ds_read_b128 v[130:133], v81 offset:160
	v_fmac_f32_e32 v135, v106, v134
	v_fmac_f32_e32 v135, v104, v136
	v_fmac_f32_e32 v135, v109, v137
	v_add_f32_e32 v140, v140, v135
	ds_read_b128 v[134:137], v81 offset:176
	s_waitcnt lgkmcnt(1)
	v_mul_f32_e32 v131, v77, v131
	v_fmac_f32_e32 v131, v5, v130
	v_fmac_f32_e32 v131, v99, v132
	v_fmac_f32_e32 v131, v105, v133
	v_add_f32_e32 v130, v140, v131
	s_waitcnt lgkmcnt(0)
	v_mul_f32_e32 v131, v100, v135
	v_fmac_f32_e32 v131, v76, v134
	v_fmac_f32_e32 v131, v102, v136
	v_fmac_f32_e32 v131, v101, v137
	v_add_f32_e32 v130, v130, v131
	v_mul_f32_e64 v131, |v130|, s43
	v_exp_f32_e32 v131, v131
	v_fmac_f32_e32 v139, 0x3377d1cf, v138
	v_fmac_f32_e32 v139, 0x3f317217, v138
	v_cmp_lt_f32_e64 s[16:17], |v138|, s46
	v_add_f32_e32 v131, 1.0, v131
	v_cndmask_b32_e32 v133, 0, v84, vcc
	v_cndmask_b32_e64 v132, v138, v139, s[16:17]
	v_cmp_gt_f32_e32 vcc, s44, v131
	v_sub_f32_e32 v132, v132, v133
	v_sub_f32_e32 v129, v129, v132
	v_cndmask_b32_e64 v133, 0, 32, vcc
	v_ldexp_f32 v131, v131, v133
	v_log_f32_e32 v138, v131
	v_min_f32_e32 v139, 0, v130
	ds_read_b128 v[130:133], v81 offset:192
	v_fmamk_f32 v129, v129, 0x3d800000, v128
	v_mul_f32_e32 v134, 0x3f317217, v138
	v_fma_f32 v140, v138, s45, -v134
	ds_read_b128 v[134:137], v81 offset:208
	s_waitcnt lgkmcnt(1)
	v_mul_f32_e32 v131, v113, v131
	v_fmac_f32_e32 v131, v110, v130
	v_fmac_f32_e32 v131, v111, v132
	v_fmac_f32_e32 v131, v112, v133
	v_add_f32_e32 v141, v117, v131
	s_waitcnt lgkmcnt(0)
	v_mul_f32_e32 v135, v107, v135
	ds_read_b128 v[130:133], v81 offset:224
	v_fmac_f32_e32 v135, v106, v134
	v_fmac_f32_e32 v135, v104, v136
	v_fmac_f32_e32 v135, v109, v137
	v_add_f32_e32 v141, v141, v135
	ds_read_b128 v[134:137], v81 offset:240
	s_waitcnt lgkmcnt(1)
	v_mul_f32_e32 v131, v77, v131
	v_fmac_f32_e32 v131, v5, v130
	v_fmac_f32_e32 v131, v99, v132
	v_fmac_f32_e32 v131, v105, v133
	v_add_f32_e32 v130, v141, v131
	s_waitcnt lgkmcnt(0)
	v_mul_f32_e32 v131, v100, v135
	v_fmac_f32_e32 v131, v76, v134
	v_fmac_f32_e32 v131, v102, v136
	v_fmac_f32_e32 v131, v101, v137
	v_add_f32_e32 v131, v130, v131
	v_mul_f32_e64 v130, |v131|, s43
	v_exp_f32_e32 v130, v130
	v_fmac_f32_e32 v140, 0x3377d1cf, v138
	v_fmac_f32_e32 v140, 0x3f317217, v138
	v_cmp_lt_f32_e64 s[16:17], |v138|, s46
	v_add_f32_e32 v130, 1.0, v130
	v_cndmask_b32_e32 v133, 0, v84, vcc
	v_cndmask_b32_e64 v132, v138, v140, s[16:17]
	v_cmp_gt_f32_e32 vcc, s44, v130
	v_sub_f32_e32 v132, v132, v133
	v_min_f32_e32 v131, 0, v131
	v_cndmask_b32_e64 v133, 0, 32, vcc
	v_ldexp_f32 v130, v130, v133
	v_log_f32_e32 v140, v130
	v_sub_f32_e32 v130, v139, v132
	ds_read_b128 v[132:135], v81 offset:256
	v_fmamk_f32 v130, v130, 0x3d800000, v129
	v_mul_f32_e32 v136, 0x3f317217, v140
	v_fma_f32 v141, v140, s45, -v136
	ds_read_b128 v[136:139], v81 offset:272
	s_waitcnt lgkmcnt(1)
	v_mul_f32_e32 v133, v113, v133
	v_fmac_f32_e32 v133, v110, v132
	v_fmac_f32_e32 v133, v111, v134
	v_fmac_f32_e32 v133, v112, v135
	v_add_f32_e32 v142, v117, v133
	s_waitcnt lgkmcnt(0)
	v_mul_f32_e32 v137, v107, v137
	ds_read_b128 v[132:135], v81 offset:288
	v_fmac_f32_e32 v137, v106, v136
	v_fmac_f32_e32 v137, v104, v138
	v_fmac_f32_e32 v137, v109, v139
	v_add_f32_e32 v142, v142, v137
	ds_read_b128 v[136:139], v81 offset:304
	s_waitcnt lgkmcnt(1)
	v_mul_f32_e32 v133, v77, v133
	v_fmac_f32_e32 v133, v5, v132
	v_fmac_f32_e32 v133, v99, v134
	v_fmac_f32_e32 v133, v105, v135
	v_add_f32_e32 v132, v142, v133
	s_waitcnt lgkmcnt(0)
	v_mul_f32_e32 v133, v100, v137
	v_fmac_f32_e32 v133, v76, v136
	v_fmac_f32_e32 v133, v102, v138
	v_fmac_f32_e32 v133, v101, v139
	v_add_f32_e32 v132, v132, v133
	v_mul_f32_e64 v133, |v132|, s43
	v_exp_f32_e32 v133, v133
	v_fmac_f32_e32 v141, 0x3377d1cf, v140
	v_fmac_f32_e32 v141, 0x3f317217, v140
	v_cmp_lt_f32_e64 s[16:17], |v140|, s46
	v_add_f32_e32 v133, 1.0, v133
	v_cndmask_b32_e32 v135, 0, v84, vcc
	v_cndmask_b32_e64 v134, v140, v141, s[16:17]
	v_cmp_gt_f32_e32 vcc, s44, v133
	v_sub_f32_e32 v134, v134, v135
	v_sub_f32_e32 v131, v131, v134
	v_cndmask_b32_e64 v135, 0, 32, vcc
	v_ldexp_f32 v133, v133, v135
	v_log_f32_e32 v140, v133
	v_min_f32_e32 v141, 0, v132
	ds_read_b128 v[132:135], v81 offset:320
	v_fmamk_f32 v131, v131, 0x3d800000, v130
	v_mul_f32_e32 v136, 0x3f317217, v140
	v_fma_f32 v142, v140, s45, -v136
	ds_read_b128 v[136:139], v81 offset:336
	s_waitcnt lgkmcnt(1)
	v_mul_f32_e32 v133, v113, v133
	v_fmac_f32_e32 v133, v110, v132
	v_fmac_f32_e32 v133, v111, v134
	v_fmac_f32_e32 v133, v112, v135
	v_add_f32_e32 v143, v117, v133
	s_waitcnt lgkmcnt(0)
	v_mul_f32_e32 v137, v107, v137
	ds_read_b128 v[132:135], v81 offset:352
	v_fmac_f32_e32 v137, v106, v136
	v_fmac_f32_e32 v137, v104, v138
	v_fmac_f32_e32 v137, v109, v139
	v_add_f32_e32 v143, v143, v137
	ds_read_b128 v[136:139], v81 offset:368
	s_waitcnt lgkmcnt(1)
	v_mul_f32_e32 v133, v77, v133
	v_fmac_f32_e32 v133, v5, v132
	v_fmac_f32_e32 v133, v99, v134
	v_fmac_f32_e32 v133, v105, v135
	v_add_f32_e32 v132, v143, v133
	s_waitcnt lgkmcnt(0)
	v_mul_f32_e32 v133, v100, v137
	v_fmac_f32_e32 v133, v76, v136
	v_fmac_f32_e32 v133, v102, v138
	v_fmac_f32_e32 v133, v101, v139
	v_add_f32_e32 v133, v132, v133
	v_mul_f32_e64 v132, |v133|, s43
	v_exp_f32_e32 v132, v132
	v_fmac_f32_e32 v142, 0x3377d1cf, v140
	v_fmac_f32_e32 v142, 0x3f317217, v140
	v_cmp_lt_f32_e64 s[16:17], |v140|, s46
	v_add_f32_e32 v132, 1.0, v132
	v_cndmask_b32_e32 v135, 0, v84, vcc
	v_cndmask_b32_e64 v134, v140, v142, s[16:17]
	v_cmp_gt_f32_e32 vcc, s44, v132
	v_sub_f32_e32 v134, v134, v135
	v_min_f32_e32 v133, 0, v133
	v_cndmask_b32_e64 v135, 0, 32, vcc
	v_ldexp_f32 v132, v132, v135
	v_log_f32_e32 v142, v132
	v_sub_f32_e32 v132, v141, v134
	ds_read_b128 v[134:137], v81 offset:384
	v_fmamk_f32 v132, v132, 0x3d800000, v131
	v_mul_f32_e32 v138, 0x3f317217, v142
	v_fma_f32 v143, v142, s45, -v138
	ds_read_b128 v[138:141], v81 offset:400
	s_waitcnt lgkmcnt(1)
	v_mul_f32_e32 v135, v113, v135
	v_fmac_f32_e32 v135, v110, v134
	v_fmac_f32_e32 v135, v111, v136
	v_fmac_f32_e32 v135, v112, v137
	v_add_f32_e32 v144, v117, v135
	s_waitcnt lgkmcnt(0)
	v_mul_f32_e32 v139, v107, v139
	ds_read_b128 v[134:137], v81 offset:416
	v_fmac_f32_e32 v139, v106, v138
	v_fmac_f32_e32 v139, v104, v140
	v_fmac_f32_e32 v139, v109, v141
	v_add_f32_e32 v144, v144, v139
	ds_read_b128 v[138:141], v81 offset:432
	s_waitcnt lgkmcnt(1)
	v_mul_f32_e32 v135, v77, v135
	v_fmac_f32_e32 v135, v5, v134
	v_fmac_f32_e32 v135, v99, v136
	v_fmac_f32_e32 v135, v105, v137
	v_add_f32_e32 v134, v144, v135
	s_waitcnt lgkmcnt(0)
	v_mul_f32_e32 v135, v100, v139
	v_fmac_f32_e32 v135, v76, v138
	v_fmac_f32_e32 v135, v102, v140
	v_fmac_f32_e32 v135, v101, v141
	v_add_f32_e32 v134, v134, v135
	v_mul_f32_e64 v135, |v134|, s43
	v_exp_f32_e32 v135, v135
	v_fmac_f32_e32 v143, 0x3377d1cf, v142
	v_fmac_f32_e32 v143, 0x3f317217, v142
	v_cmp_lt_f32_e64 s[16:17], |v142|, s46
	v_add_f32_e32 v135, 1.0, v135
	v_cndmask_b32_e32 v137, 0, v84, vcc
	v_cndmask_b32_e64 v136, v142, v143, s[16:17]
	v_cmp_gt_f32_e32 vcc, s44, v135
	v_sub_f32_e32 v136, v136, v137
	v_sub_f32_e32 v133, v133, v136
	v_cndmask_b32_e64 v137, 0, 32, vcc
	v_ldexp_f32 v135, v135, v137
	v_log_f32_e32 v142, v135
	v_min_f32_e32 v143, 0, v134
	ds_read_b128 v[134:137], v81 offset:448
	v_fmamk_f32 v133, v133, 0x3d800000, v132
	v_mul_f32_e32 v138, 0x3f317217, v142
	v_fma_f32 v144, v142, s45, -v138
	ds_read_b128 v[138:141], v81 offset:464
	s_waitcnt lgkmcnt(1)
	v_mul_f32_e32 v135, v113, v135
	v_fmac_f32_e32 v135, v110, v134
	v_fmac_f32_e32 v135, v111, v136
	v_fmac_f32_e32 v135, v112, v137
	v_add_f32_e32 v145, v117, v135
	s_waitcnt lgkmcnt(0)
	v_mul_f32_e32 v139, v107, v139
	ds_read_b128 v[134:137], v81 offset:480
	v_fmac_f32_e32 v139, v106, v138
	v_fmac_f32_e32 v139, v104, v140
	v_fmac_f32_e32 v139, v109, v141
	v_add_f32_e32 v145, v145, v139
	ds_read_b128 v[138:141], v81 offset:496
	s_waitcnt lgkmcnt(1)
	v_mul_f32_e32 v135, v77, v135
	v_fmac_f32_e32 v135, v5, v134
	v_fmac_f32_e32 v135, v99, v136
	v_fmac_f32_e32 v135, v105, v137
	v_add_f32_e32 v134, v145, v135
	s_waitcnt lgkmcnt(0)
	v_mul_f32_e32 v135, v100, v139
	v_fmac_f32_e32 v135, v76, v138
	v_fmac_f32_e32 v135, v102, v140
	v_fmac_f32_e32 v135, v101, v141
	v_add_f32_e32 v135, v134, v135
	v_mul_f32_e64 v134, |v135|, s43
	v_exp_f32_e32 v134, v134
	v_fmac_f32_e32 v144, 0x3377d1cf, v142
	v_fmac_f32_e32 v144, 0x3f317217, v142
	v_cmp_lt_f32_e64 s[16:17], |v142|, s46
	v_add_f32_e32 v134, 1.0, v134
	v_cndmask_b32_e32 v137, 0, v84, vcc
	v_cndmask_b32_e64 v136, v142, v144, s[16:17]
	v_cmp_gt_f32_e32 vcc, s44, v134
	v_sub_f32_e32 v136, v136, v137
	v_min_f32_e32 v135, 0, v135
	v_cndmask_b32_e64 v137, 0, 32, vcc
	v_ldexp_f32 v134, v134, v137
	v_log_f32_e32 v144, v134
	v_sub_f32_e32 v134, v143, v136
	ds_read_b128 v[136:139], v81 offset:512
	v_fmamk_f32 v134, v134, 0x3d800000, v133
	v_mul_f32_e32 v140, 0x3f317217, v144
	v_fma_f32 v145, v144, s45, -v140
	ds_read_b128 v[140:143], v81 offset:528
	s_waitcnt lgkmcnt(1)
	v_mul_f32_e32 v137, v113, v137
	v_fmac_f32_e32 v137, v110, v136
	v_fmac_f32_e32 v137, v111, v138
	v_fmac_f32_e32 v137, v112, v139
	v_add_f32_e32 v146, v117, v137
	s_waitcnt lgkmcnt(0)
	v_mul_f32_e32 v141, v107, v141
	ds_read_b128 v[136:139], v81 offset:544
	v_fmac_f32_e32 v141, v106, v140
	v_fmac_f32_e32 v141, v104, v142
	v_fmac_f32_e32 v141, v109, v143
	v_add_f32_e32 v146, v146, v141
	ds_read_b128 v[140:143], v81 offset:560
	s_waitcnt lgkmcnt(1)
	v_mul_f32_e32 v137, v77, v137
	v_fmac_f32_e32 v137, v5, v136
	v_fmac_f32_e32 v137, v99, v138
	v_fmac_f32_e32 v137, v105, v139
	v_add_f32_e32 v136, v146, v137
	s_waitcnt lgkmcnt(0)
	v_mul_f32_e32 v137, v100, v141
	v_fmac_f32_e32 v137, v76, v140
	v_fmac_f32_e32 v137, v102, v142
	v_fmac_f32_e32 v137, v101, v143
	v_add_f32_e32 v136, v136, v137
	v_mul_f32_e64 v137, |v136|, s43
	v_exp_f32_e32 v137, v137
	v_fmac_f32_e32 v145, 0x3377d1cf, v144
	v_fmac_f32_e32 v145, 0x3f317217, v144
	v_cmp_lt_f32_e64 s[16:17], |v144|, s46
	v_add_f32_e32 v137, 1.0, v137
	v_cndmask_b32_e32 v139, 0, v84, vcc
	v_cndmask_b32_e64 v138, v144, v145, s[16:17]
	v_cmp_gt_f32_e32 vcc, s44, v137
	v_sub_f32_e32 v138, v138, v139
	v_sub_f32_e32 v135, v135, v138
	v_cndmask_b32_e64 v139, 0, 32, vcc
	v_ldexp_f32 v137, v137, v139
	v_log_f32_e32 v144, v137
	v_min_f32_e32 v145, 0, v136
	ds_read_b128 v[136:139], v81 offset:576
	v_fmamk_f32 v135, v135, 0x3d800000, v134
	v_mul_f32_e32 v140, 0x3f317217, v144
	v_fma_f32 v146, v144, s45, -v140
	ds_read_b128 v[140:143], v81 offset:592
	s_waitcnt lgkmcnt(1)
	v_mul_f32_e32 v137, v113, v137
	v_fmac_f32_e32 v137, v110, v136
	v_fmac_f32_e32 v137, v111, v138
	v_fmac_f32_e32 v137, v112, v139
	v_add_f32_e32 v147, v117, v137
	s_waitcnt lgkmcnt(0)
	v_mul_f32_e32 v141, v107, v141
	ds_read_b128 v[136:139], v81 offset:608
	v_fmac_f32_e32 v141, v106, v140
	v_fmac_f32_e32 v141, v104, v142
	v_fmac_f32_e32 v141, v109, v143
	v_add_f32_e32 v147, v147, v141
	ds_read_b128 v[140:143], v81 offset:624
	s_waitcnt lgkmcnt(1)
	v_mul_f32_e32 v137, v77, v137
	v_fmac_f32_e32 v137, v5, v136
	v_fmac_f32_e32 v137, v99, v138
	v_fmac_f32_e32 v137, v105, v139
	v_add_f32_e32 v136, v147, v137
	s_waitcnt lgkmcnt(0)
	v_mul_f32_e32 v137, v100, v141
	v_fmac_f32_e32 v137, v76, v140
	v_fmac_f32_e32 v137, v102, v142
	v_fmac_f32_e32 v137, v101, v143
	v_add_f32_e32 v137, v136, v137
	v_mul_f32_e64 v136, |v137|, s43
	v_exp_f32_e32 v136, v136
	v_fmac_f32_e32 v146, 0x3377d1cf, v144
	v_fmac_f32_e32 v146, 0x3f317217, v144
	v_cmp_lt_f32_e64 s[16:17], |v144|, s46
	v_add_f32_e32 v136, 1.0, v136
	v_cndmask_b32_e32 v139, 0, v84, vcc
	v_cndmask_b32_e64 v138, v144, v146, s[16:17]
	v_cmp_gt_f32_e32 vcc, s44, v136
	v_sub_f32_e32 v138, v138, v139
	v_min_f32_e32 v137, 0, v137
	v_cndmask_b32_e64 v139, 0, 32, vcc
	v_ldexp_f32 v136, v136, v139
	v_log_f32_e32 v146, v136
	v_sub_f32_e32 v136, v145, v138
	ds_read_b128 v[138:141], v81 offset:640
	v_fmamk_f32 v136, v136, 0x3d800000, v135
	v_mul_f32_e32 v142, 0x3f317217, v146
	v_fma_f32 v147, v146, s45, -v142
	ds_read_b128 v[142:145], v81 offset:656
	s_waitcnt lgkmcnt(1)
	v_mul_f32_e32 v139, v113, v139
	v_fmac_f32_e32 v139, v110, v138
	v_fmac_f32_e32 v139, v111, v140
	v_fmac_f32_e32 v139, v112, v141
	v_add_f32_e32 v148, v117, v139
	s_waitcnt lgkmcnt(0)
	v_mul_f32_e32 v143, v107, v143
	ds_read_b128 v[138:141], v81 offset:672
	v_fmac_f32_e32 v143, v106, v142
	v_fmac_f32_e32 v143, v104, v144
	v_fmac_f32_e32 v143, v109, v145
	v_add_f32_e32 v148, v148, v143
	ds_read_b128 v[142:145], v81 offset:688
	s_waitcnt lgkmcnt(1)
	v_mul_f32_e32 v139, v77, v139
	v_fmac_f32_e32 v139, v5, v138
	v_fmac_f32_e32 v139, v99, v140
	v_fmac_f32_e32 v139, v105, v141
	v_add_f32_e32 v138, v148, v139
	s_waitcnt lgkmcnt(0)
	v_mul_f32_e32 v139, v100, v143
	v_fmac_f32_e32 v139, v76, v142
	v_fmac_f32_e32 v139, v102, v144
	v_fmac_f32_e32 v139, v101, v145
	v_add_f32_e32 v138, v138, v139
	v_mul_f32_e64 v139, |v138|, s43
	v_exp_f32_e32 v139, v139
	v_fmac_f32_e32 v147, 0x3377d1cf, v146
	v_fmac_f32_e32 v147, 0x3f317217, v146
	v_cmp_lt_f32_e64 s[16:17], |v146|, s46
	v_add_f32_e32 v139, 1.0, v139
	v_cndmask_b32_e32 v141, 0, v84, vcc
	v_cndmask_b32_e64 v140, v146, v147, s[16:17]
	v_cmp_gt_f32_e32 vcc, s44, v139
	v_sub_f32_e32 v140, v140, v141
	v_sub_f32_e32 v137, v137, v140
	v_cndmask_b32_e64 v141, 0, 32, vcc
	v_ldexp_f32 v139, v139, v141
	v_log_f32_e32 v146, v139
	v_min_f32_e32 v147, 0, v138
	ds_read_b128 v[138:141], v81 offset:704
	v_fmamk_f32 v137, v137, 0x3d800000, v136
	v_mul_f32_e32 v142, 0x3f317217, v146
	v_fma_f32 v148, v146, s45, -v142
	ds_read_b128 v[142:145], v81 offset:720
	s_waitcnt lgkmcnt(1)
	v_mul_f32_e32 v139, v113, v139
	v_fmac_f32_e32 v139, v110, v138
	v_fmac_f32_e32 v139, v111, v140
	v_fmac_f32_e32 v139, v112, v141
	v_add_f32_e32 v149, v117, v139
	s_waitcnt lgkmcnt(0)
	v_mul_f32_e32 v143, v107, v143
	ds_read_b128 v[138:141], v81 offset:736
	v_fmac_f32_e32 v143, v106, v142
	v_fmac_f32_e32 v143, v104, v144
	v_fmac_f32_e32 v143, v109, v145
	v_add_f32_e32 v149, v149, v143
	ds_read_b128 v[142:145], v81 offset:752
	s_waitcnt lgkmcnt(1)
	v_mul_f32_e32 v139, v77, v139
	v_fmac_f32_e32 v139, v5, v138
	v_fmac_f32_e32 v139, v99, v140
	v_fmac_f32_e32 v139, v105, v141
	v_add_f32_e32 v138, v149, v139
	s_waitcnt lgkmcnt(0)
	v_mul_f32_e32 v139, v100, v143
	v_fmac_f32_e32 v139, v76, v142
	v_fmac_f32_e32 v139, v102, v144
	v_fmac_f32_e32 v139, v101, v145
	v_add_f32_e32 v139, v138, v139
	v_mul_f32_e64 v138, |v139|, s43
	v_exp_f32_e32 v138, v138
	v_fmac_f32_e32 v148, 0x3377d1cf, v146
	v_fmac_f32_e32 v148, 0x3f317217, v146
	v_cmp_lt_f32_e64 s[16:17], |v146|, s46
	v_add_f32_e32 v138, 1.0, v138
	v_cndmask_b32_e32 v141, 0, v84, vcc
	v_cndmask_b32_e64 v140, v146, v148, s[16:17]
	v_cmp_gt_f32_e32 vcc, s44, v138
	v_sub_f32_e32 v140, v140, v141
	v_min_f32_e32 v139, 0, v139
	v_cndmask_b32_e64 v141, 0, 32, vcc
	v_ldexp_f32 v138, v138, v141
	v_log_f32_e32 v148, v138
	v_sub_f32_e32 v138, v147, v140
	ds_read_b128 v[140:143], v81 offset:768
	v_fmamk_f32 v138, v138, 0x3d800000, v137
	v_mul_f32_e32 v144, 0x3f317217, v148
	v_fma_f32 v149, v148, s45, -v144
	ds_read_b128 v[144:147], v81 offset:784
	s_waitcnt lgkmcnt(1)
	v_mul_f32_e32 v141, v113, v141
	v_fmac_f32_e32 v141, v110, v140
	v_fmac_f32_e32 v141, v111, v142
	v_fmac_f32_e32 v141, v112, v143
	v_add_f32_e32 v150, v117, v141
	s_waitcnt lgkmcnt(0)
	v_mul_f32_e32 v145, v107, v145
	ds_read_b128 v[140:143], v81 offset:800
	v_fmac_f32_e32 v145, v106, v144
	v_fmac_f32_e32 v145, v104, v146
	v_fmac_f32_e32 v145, v109, v147
	v_add_f32_e32 v150, v150, v145
	ds_read_b128 v[144:147], v81 offset:816
	s_waitcnt lgkmcnt(1)
	v_mul_f32_e32 v141, v77, v141
	v_fmac_f32_e32 v141, v5, v140
	v_fmac_f32_e32 v141, v99, v142
	v_fmac_f32_e32 v141, v105, v143
	v_add_f32_e32 v140, v150, v141
	s_waitcnt lgkmcnt(0)
	v_mul_f32_e32 v141, v100, v145
	v_fmac_f32_e32 v141, v76, v144
	v_fmac_f32_e32 v141, v102, v146
	v_fmac_f32_e32 v141, v101, v147
	v_add_f32_e32 v140, v140, v141
	v_mul_f32_e64 v141, |v140|, s43
	v_exp_f32_e32 v141, v141
	v_fmac_f32_e32 v149, 0x3377d1cf, v148
	v_fmac_f32_e32 v149, 0x3f317217, v148
	v_cmp_lt_f32_e64 s[16:17], |v148|, s46
	v_add_f32_e32 v141, 1.0, v141
	v_cndmask_b32_e32 v143, 0, v84, vcc
	v_cndmask_b32_e64 v142, v148, v149, s[16:17]
	v_cmp_gt_f32_e32 vcc, s44, v141
	v_sub_f32_e32 v142, v142, v143
	v_sub_f32_e32 v139, v139, v142
	v_cndmask_b32_e64 v143, 0, 32, vcc
	v_ldexp_f32 v141, v141, v143
	v_log_f32_e32 v148, v141
	v_min_f32_e32 v149, 0, v140
	ds_read_b128 v[140:143], v81 offset:832
	v_fmamk_f32 v139, v139, 0x3d800000, v138
	v_mul_f32_e32 v144, 0x3f317217, v148
	v_fma_f32 v150, v148, s45, -v144
	ds_read_b128 v[144:147], v81 offset:848
	s_waitcnt lgkmcnt(1)
	v_mul_f32_e32 v141, v113, v141
	v_fmac_f32_e32 v141, v110, v140
	v_fmac_f32_e32 v141, v111, v142
	v_fmac_f32_e32 v141, v112, v143
	v_add_f32_e32 v151, v117, v141
	s_waitcnt lgkmcnt(0)
	v_mul_f32_e32 v145, v107, v145
	ds_read_b128 v[140:143], v81 offset:864
	v_fmac_f32_e32 v145, v106, v144
	v_fmac_f32_e32 v145, v104, v146
	v_fmac_f32_e32 v145, v109, v147
	v_add_f32_e32 v151, v151, v145
	ds_read_b128 v[144:147], v81 offset:880
	s_waitcnt lgkmcnt(1)
	v_mul_f32_e32 v141, v77, v141
	v_fmac_f32_e32 v141, v5, v140
	v_fmac_f32_e32 v141, v99, v142
	v_fmac_f32_e32 v141, v105, v143
	v_add_f32_e32 v140, v151, v141
	s_waitcnt lgkmcnt(0)
	v_mul_f32_e32 v141, v100, v145
	v_fmac_f32_e32 v141, v76, v144
	v_fmac_f32_e32 v141, v102, v146
	v_fmac_f32_e32 v141, v101, v147
	v_add_f32_e32 v140, v140, v141
	v_mul_f32_e64 v141, |v140|, s43
	v_exp_f32_e32 v141, v141
	v_fmac_f32_e32 v150, 0x3377d1cf, v148
	v_fmac_f32_e32 v150, 0x3f317217, v148
	v_cmp_lt_f32_e64 s[16:17], |v148|, s46
	v_add_f32_e32 v141, 1.0, v141
	v_cndmask_b32_e32 v143, 0, v84, vcc
	v_cndmask_b32_e64 v142, v148, v150, s[16:17]
	v_cmp_gt_f32_e32 vcc, s44, v141
	v_sub_f32_e32 v142, v142, v143
	v_min_f32_e32 v150, 0, v140
	v_cndmask_b32_e64 v143, 0, 32, vcc
	v_ldexp_f32 v141, v141, v143
	v_log_f32_e32 v148, v141
	v_sub_f32_e32 v141, v149, v142
	v_fmamk_f32 v149, v141, 0x3d800000, v139
	ds_read_b128 v[140:143], v81 offset:896
	v_mul_f32_e32 v144, 0x3f317217, v148
	v_fma_f32 v151, v148, s45, -v144
	ds_read_b128 v[144:147], v81 offset:912
	v_fmac_f32_e32 v151, 0x3377d1cf, v148
	s_waitcnt lgkmcnt(1)
	v_mul_f32_e32 v141, v113, v141
	v_fmac_f32_e32 v141, v110, v140
	v_fmac_f32_e32 v141, v111, v142
	v_fmac_f32_e32 v141, v112, v143
	v_add_f32_e32 v152, v117, v141
	s_waitcnt lgkmcnt(0)
	v_mul_f32_e32 v145, v107, v145
	ds_read_b128 v[140:143], v81 offset:928
	v_fmac_f32_e32 v145, v106, v144
	v_fmac_f32_e32 v145, v104, v146
	v_fmac_f32_e32 v145, v109, v147
	v_add_f32_e32 v152, v152, v145
	ds_read_b128 v[144:147], v81 offset:944
	s_waitcnt lgkmcnt(1)
	v_mul_f32_e32 v141, v77, v141
	v_fmac_f32_e32 v141, v5, v140
	v_fmac_f32_e32 v141, v99, v142
	v_fmac_f32_e32 v141, v105, v143
	v_add_f32_e32 v140, v152, v141
	s_waitcnt lgkmcnt(0)
	v_mul_f32_e32 v141, v100, v145
	v_fmac_f32_e32 v141, v76, v144
	v_fmac_f32_e32 v141, v102, v146
	v_fmac_f32_e32 v141, v101, v147
	v_add_f32_e32 v140, v140, v141
	v_mul_f32_e64 v141, |v140|, s43
	v_exp_f32_e32 v141, v141
	v_fmac_f32_e32 v151, 0x3f317217, v148
	v_cmp_lt_f32_e64 s[16:17], |v148|, s46
	v_cndmask_b32_e32 v143, 0, v84, vcc
	v_add_f32_e32 v141, 1.0, v141
	v_cndmask_b32_e64 v142, v148, v151, s[16:17]
	v_cmp_gt_f32_e32 vcc, s44, v141
	v_sub_f32_e32 v142, v142, v143
	v_min_f32_e32 v151, 0, v140
	v_cndmask_b32_e64 v143, 0, 32, vcc
	v_ldexp_f32 v141, v141, v143
	v_log_f32_e32 v148, v141
	v_sub_f32_e32 v141, v150, v142
	v_fmamk_f32 v150, v141, 0x3d800000, v149
	ds_read_b128 v[140:143], v81 offset:960
	v_mul_f32_e32 v144, 0x3f317217, v148
	v_fma_f32 v152, v148, s45, -v144
	ds_read_b128 v[144:147], v81 offset:976
	v_fmac_f32_e32 v152, 0x3377d1cf, v148
	s_waitcnt lgkmcnt(1)
	v_mul_f32_e32 v113, v113, v141
	v_fmac_f32_e32 v113, v110, v140
	v_fmac_f32_e32 v113, v111, v142
	v_fmac_f32_e32 v113, v112, v143
	v_add_f32_e32 v117, v117, v113
	ds_read_b128 v[110:113], v81 offset:992
	ds_read_b128 v[140:143], v81 offset:1008
	s_waitcnt lgkmcnt(2)
	v_mul_f32_e32 v107, v107, v145
	v_fmac_f32_e32 v107, v106, v144
	v_fmac_f32_e32 v107, v104, v146
	s_waitcnt lgkmcnt(1)
	v_mul_f32_e32 v77, v77, v111
	v_fmac_f32_e32 v77, v5, v110
	v_fmac_f32_e32 v107, v109, v147
	v_fmac_f32_e32 v77, v99, v112
	v_add_f32_e32 v104, v117, v107
	v_fmac_f32_e32 v77, v105, v113
	v_add_f32_e32 v5, v104, v77
	s_waitcnt lgkmcnt(0)
	v_mul_f32_e32 v77, v100, v141
	v_fmac_f32_e32 v77, v76, v140
	v_fmac_f32_e32 v77, v102, v142
	v_fmac_f32_e32 v77, v101, v143
	v_add_f32_e32 v5, v5, v77
	v_mul_f32_e64 v76, |v5|, s43
	v_exp_f32_e32 v76, v76
	v_fmac_f32_e32 v152, 0x3f317217, v148
	v_cmp_lt_f32_e64 s[16:17], |v148|, s46
	v_cndmask_b32_e32 v99, 0, v84, vcc
	v_add_f32_e32 v76, 1.0, v76
	v_cndmask_b32_e64 v77, v148, v152, s[16:17]
	v_cmp_gt_f32_e32 vcc, s44, v76
	v_sub_f32_e32 v77, v77, v99
	v_sub_f32_e32 v77, v151, v77
	v_cndmask_b32_e64 v99, 0, 32, vcc
	v_ldexp_f32 v76, v76, v99
	v_log_f32_e32 v76, v76
	v_fmamk_f32 v102, v77, 0x3d800000, v150
	v_min_f32_e32 v5, 0, v5
	v_lshlrev_b64 v[72:73], 10, v[72:73]
	v_mul_f32_e32 v77, 0x3f317217, v76
	v_fma_f32 v77, v76, s45, -v77
	v_fmac_f32_e32 v77, 0x3377d1cf, v76
	v_fmac_f32_e32 v77, 0x3f317217, v76
	v_cmp_lt_f32_e64 s[16:17], |v76|, s46
	v_ashrrev_i32_e32 v69, 31, v68
	v_lshlrev_b64 v[68:69], 10, v[68:69]
	v_cndmask_b32_e64 v76, v76, v77, s[16:17]
	v_cndmask_b32_e32 v77, 0, v84, vcc
	v_sub_f32_e32 v76, v76, v77
	v_sub_f32_e32 v5, v5, v76
	v_fmamk_f32 v104, v5, 0x3d800000, v102
	ds_write_b32 v82, v104 offset:4096
	s_waitcnt lgkmcnt(0)
	s_barrier
	ds_read2st64_b32 v[76:77], v83 offset0:16 offset1:18
	ds_read2st64_b32 v[100:101], v83 offset0:20 offset1:22
	s_add_u32 s16, s28, s24
	s_addc_u32 s17, s29, 0
	v_ashrrev_i32_e32 v65, 31, v64
	s_waitcnt lgkmcnt(1)
	v_add_f32_e32 v5, 0, v76
	v_cndmask_b32_e64 v76, v5, 0, s[8:9]
	v_add_f32_e32 v5, v5, v77
	v_add_f32_e32 v77, v77, v76
	v_cndmask_b32_e64 v76, v76, v77, s[10:11]
	s_waitcnt lgkmcnt(0)
	v_add_f32_e32 v77, v100, v76
	v_add_f32_e32 v5, v5, v100
	v_cndmask_b32_e64 v76, v76, v77, s[12:13]
	v_add_f32_e32 v5, v5, v101
	v_add_f32_e32 v77, v101, v76
	v_cndmask_b32_e64 v100, v76, v77, s[14:15]
	v_mul_f32_e32 v5, 0x3fb8aa3b, v5
	v_exp_f32_e32 v99, v5
	v_add_f32_e32 v5, v128, v100
	v_mul_f32_e32 v5, 0x3fb8aa3b, v5
	v_exp_f32_e32 v101, v5
	v_mov_b32_e32 v5, v3
	v_lshl_add_u64 v[76:77], s[16:17], 0, v[4:5]
	v_lshlrev_b32_e32 v5, 16, v98
	v_rcp_f32_e32 v98, v101
	v_mul_f32_e32 v5, v101, v5
	v_cvt_pk_bf16_f32 v5, v5, s0
	ds_write_b16 v178, v5
	v_mul_f32_e32 v5, v98, v127
	v_cvt_pk_bf16_f32 v5, v5, s0
	ds_write_b16 v178, v5 offset:256
	v_add_f32_e32 v74, v129, v100
	v_mul_f32_e32 v74, 0x3fb8aa3b, v74
	v_exp_f32_e32 v74, v74
	v_mul_f32_e32 v5, v99, v98
	v_mul_f32_e32 v5, v5, v127
	v_cvt_pk_bf16_f32 v5, v5, s0
	v_lshl_add_u64 v[72:73], v[76:77], 0, v[72:73]
	ds_write_b16 v178, v5 offset:512
	v_rcp_f32_e32 v72, v74
	v_lshlrev_b32_e32 v5, 16, v97
	v_mul_f32_e32 v5, v74, v5
	v_cvt_pk_bf16_f32 v5, v5, s0
	ds_write_b16 v178, v5 offset:768
	v_mul_f32_e32 v5, v72, v126
	v_cvt_pk_bf16_f32 v5, v5, s0
	ds_write_b16 v178, v5 offset:1024
	v_add_f32_e32 v70, v130, v100
	v_mul_f32_e32 v70, 0x3fb8aa3b, v70
	v_exp_f32_e32 v70, v70
	v_mul_f32_e32 v5, v99, v72
	v_mul_f32_e32 v5, v5, v126
	v_cvt_pk_bf16_f32 v5, v5, s0
	v_lshl_add_u64 v[68:69], v[76:77], 0, v[68:69]
	ds_write_b16 v178, v5 offset:1280
	v_rcp_f32_e32 v68, v70
	v_lshlrev_b32_e32 v5, 16, v96
	v_mul_f32_e32 v5, v70, v5
	v_cvt_pk_bf16_f32 v5, v5, s0
	ds_write_b16 v178, v5 offset:1536
	v_mul_f32_e32 v5, v68, v124
	v_cvt_pk_bf16_f32 v5, v5, s0
	ds_write_b16 v178, v5 offset:1792
	v_add_f32_e32 v66, v131, v100
	v_mul_f32_e32 v66, 0x3fb8aa3b, v66
	v_exp_f32_e32 v66, v66
	v_mul_f32_e32 v5, v99, v68
	v_mul_f32_e32 v5, v5, v124
	v_lshlrev_b64 v[64:65], 10, v[64:65]
	v_cvt_pk_bf16_f32 v5, v5, s0
	v_lshl_add_u64 v[64:65], v[76:77], 0, v[64:65]
	ds_write_b16 v178, v5 offset:2048
	v_rcp_f32_e32 v64, v66
	v_lshlrev_b32_e32 v5, 16, v94
	v_mul_f32_e32 v5, v66, v5
	v_cvt_pk_bf16_f32 v5, v5, s0
	ds_write_b16 v178, v5 offset:2304
	v_mul_f32_e32 v5, v64, v120
	v_cvt_pk_bf16_f32 v5, v5, s0
	ds_write_b16 v178, v5 offset:2560
	v_add_f32_e32 v62, v132, v100
	v_mul_f32_e32 v62, 0x3fb8aa3b, v62
	v_exp_f32_e32 v62, v62
	v_ashrrev_i32_e32 v61, 31, v60
	v_mul_f32_e32 v5, v99, v64
	v_mul_f32_e32 v5, v5, v120
	v_lshlrev_b64 v[60:61], 10, v[60:61]
	v_cvt_pk_bf16_f32 v5, v5, s0
	v_lshl_add_u64 v[60:61], v[76:77], 0, v[60:61]
	ds_write_b16 v178, v5 offset:2816
	v_rcp_f32_e32 v60, v62
	v_lshlrev_b32_e32 v5, 16, v95
	v_mul_f32_e32 v5, v62, v5
	v_lshlrev_b32_e32 v119, 16, v119
	v_cvt_pk_bf16_f32 v5, v5, s0
	ds_write_b16 v178, v5 offset:3072
	v_mul_f32_e32 v5, v60, v119
	v_cvt_pk_bf16_f32 v5, v5, s0
	ds_write_b16 v178, v5 offset:3328
	v_add_f32_e32 v58, v133, v100
	v_mul_f32_e32 v58, 0x3fb8aa3b, v58
	v_exp_f32_e32 v58, v58
	v_ashrrev_i32_e32 v57, 31, v56
	v_mul_f32_e32 v5, v99, v60
	v_mul_f32_e32 v5, v5, v119
	v_lshlrev_b64 v[56:57], 10, v[56:57]
	v_cvt_pk_bf16_f32 v5, v5, s0
	v_lshl_add_u64 v[56:57], v[76:77], 0, v[56:57]
	ds_write_b16 v178, v5 offset:3584
	v_rcp_f32_e32 v56, v58
	v_lshlrev_b32_e32 v5, 16, v93
	v_mul_f32_e32 v5, v58, v5
	v_cvt_pk_bf16_f32 v5, v5, s0
	ds_write_b16 v178, v5 offset:3840
	v_mul_f32_e32 v5, v56, v116
	v_cvt_pk_bf16_f32 v5, v5, s0
	ds_write_b16 v178, v5 offset:4096
	v_add_f32_e32 v54, v134, v100
	v_mul_f32_e32 v54, 0x3fb8aa3b, v54
	v_exp_f32_e32 v54, v54
	v_ashrrev_i32_e32 v53, 31, v52
	v_mul_f32_e32 v5, v99, v56
	v_mul_f32_e32 v5, v5, v116
	v_lshlrev_b64 v[52:53], 10, v[52:53]
	v_cvt_pk_bf16_f32 v5, v5, s0
	v_lshl_add_u64 v[52:53], v[76:77], 0, v[52:53]
	ds_write_b16 v178, v5 offset:4352
	v_rcp_f32_e32 v52, v54
	v_lshlrev_b32_e32 v5, 16, v92
	v_mul_f32_e32 v5, v54, v5
	v_cvt_pk_bf16_f32 v5, v5, s0
	ds_write_b16 v178, v5 offset:4608
	v_mul_f32_e32 v5, v52, v114
	v_cvt_pk_bf16_f32 v5, v5, s0
	ds_write_b16 v178, v5 offset:4864
	v_add_f32_e32 v50, v135, v100
	v_mul_f32_e32 v50, 0x3fb8aa3b, v50
	v_exp_f32_e32 v50, v50
	v_ashrrev_i32_e32 v49, 31, v48
	v_mul_f32_e32 v5, v99, v52
	v_mul_f32_e32 v5, v5, v114
	v_lshlrev_b64 v[48:49], 10, v[48:49]
	v_cvt_pk_bf16_f32 v5, v5, s0
	v_lshl_add_u64 v[48:49], v[76:77], 0, v[48:49]
	ds_write_b16 v178, v5 offset:5120
	v_rcp_f32_e32 v48, v50
	v_lshlrev_b32_e32 v5, 16, v90
	v_mul_f32_e32 v5, v50, v5
	v_cvt_pk_bf16_f32 v5, v5, s0
	ds_write_b16 v178, v5 offset:5376
	v_mul_f32_e32 v5, v48, v118
	v_cvt_pk_bf16_f32 v5, v5, s0
	ds_write_b16 v178, v5 offset:5632
	v_add_f32_e32 v46, v136, v100
	v_mul_f32_e32 v46, 0x3fb8aa3b, v46
	v_exp_f32_e32 v46, v46
	v_ashrrev_i32_e32 v45, 31, v44
	v_mul_f32_e32 v5, v99, v48
	v_mul_f32_e32 v5, v5, v118
	v_lshlrev_b64 v[44:45], 10, v[44:45]
	v_cvt_pk_bf16_f32 v5, v5, s0
	v_lshl_add_u64 v[44:45], v[76:77], 0, v[44:45]
	ds_write_b16 v178, v5 offset:5888
	v_rcp_f32_e32 v44, v46
	v_lshlrev_b32_e32 v5, 16, v91
	v_mul_f32_e32 v5, v46, v5
	v_lshlrev_b32_e32 v115, 16, v115
	v_cvt_pk_bf16_f32 v5, v5, s0
	ds_write_b16 v178, v5 offset:6144
	v_mul_f32_e32 v5, v44, v115
	v_cvt_pk_bf16_f32 v5, v5, s0
	ds_write_b16 v178, v5 offset:6400
	v_add_f32_e32 v42, v137, v100
	v_mul_f32_e32 v42, 0x3fb8aa3b, v42
	v_exp_f32_e32 v42, v42
	v_ashrrev_i32_e32 v41, 31, v40
	v_mul_f32_e32 v5, v99, v44
	v_mul_f32_e32 v5, v5, v115
	v_lshlrev_b64 v[40:41], 10, v[40:41]
	v_cvt_pk_bf16_f32 v5, v5, s0
	v_lshl_add_u64 v[40:41], v[76:77], 0, v[40:41]
	ds_write_b16 v178, v5 offset:6656
	v_rcp_f32_e32 v40, v42
	v_lshlrev_b32_e32 v5, 16, v89
	v_mul_f32_e32 v5, v42, v5
	v_cvt_pk_bf16_f32 v5, v5, s0
	ds_write_b16 v178, v5 offset:6912
	v_mul_f32_e32 v5, v40, v108
	v_cvt_pk_bf16_f32 v5, v5, s0
	ds_write_b16 v178, v5 offset:7168
	v_add_f32_e32 v38, v138, v100
	v_mul_f32_e32 v38, 0x3fb8aa3b, v38
	v_exp_f32_e32 v38, v38
	v_ashrrev_i32_e32 v37, 31, v36
	v_mul_f32_e32 v5, v99, v40
	v_mul_f32_e32 v5, v5, v108
	v_lshlrev_b64 v[36:37], 10, v[36:37]
	v_cvt_pk_bf16_f32 v5, v5, s0
	v_lshl_add_u64 v[36:37], v[76:77], 0, v[36:37]
	ds_write_b16 v178, v5 offset:7424
	v_rcp_f32_e32 v36, v38
	v_lshlrev_b32_e32 v5, 16, v88
	v_mul_f32_e32 v5, v38, v5
	v_cvt_pk_bf16_f32 v5, v5, s0
	ds_write_b16 v178, v5 offset:7680
	v_mul_f32_e32 v5, v36, v103
	v_cvt_pk_bf16_f32 v5, v5, s0
	ds_write_b16 v178, v5 offset:7936
	v_add_f32_e32 v34, v139, v100
	v_mul_f32_e32 v34, 0x3fb8aa3b, v34
	v_exp_f32_e32 v34, v34
	v_ashrrev_i32_e32 v33, 31, v32
	v_mul_f32_e32 v5, v99, v36
	v_mul_f32_e32 v5, v5, v103
	v_lshlrev_b64 v[32:33], 10, v[32:33]
	v_cvt_pk_bf16_f32 v5, v5, s0
	v_lshl_add_u64 v[32:33], v[76:77], 0, v[32:33]
	ds_write_b16 v178, v5 offset:8192
	v_rcp_f32_e32 v32, v34
	v_lshlrev_b32_e32 v5, 16, v86
	v_mul_f32_e32 v5, v34, v5
	v_cvt_pk_bf16_f32 v5, v5, s0
	ds_write_b16 v178, v5 offset:8448
	v_mul_f32_e32 v5, v32, v9
	v_cvt_pk_bf16_f32 v5, v5, s0
	ds_write_b16 v178, v5 offset:8704
	v_mul_f32_e32 v5, v99, v32
	v_mul_f32_e32 v5, v5, v9
	v_add_f32_e32 v9, v149, v100
	v_mul_f32_e32 v9, 0x3fb8aa3b, v9
	v_exp_f32_e32 v9, v9
	v_ashrrev_i32_e32 v29, 31, v28
	v_lshlrev_b64 v[28:29], 10, v[28:29]
	v_cvt_pk_bf16_f32 v5, v5, s0
	v_lshl_add_u64 v[28:29], v[76:77], 0, v[28:29]
	ds_write_b16 v178, v5 offset:8960
	v_rcp_f32_e32 v28, v9
	v_lshlrev_b32_e32 v5, 16, v87
	v_mul_f32_e32 v5, v9, v5
	v_lshlrev_b32_e32 v105, 16, v121
	v_cvt_pk_bf16_f32 v5, v5, s0
	v_add_f32_e32 v9, v150, v100
	ds_write_b16 v178, v5 offset:9216
	v_mul_f32_e32 v5, v28, v105
	v_mul_f32_e32 v9, 0x3fb8aa3b, v9
	v_cvt_pk_bf16_f32 v5, v5, s0
	v_exp_f32_e32 v9, v9
	v_ashrrev_i32_e32 v25, 31, v24
	ds_write_b16 v178, v5 offset:9472
	v_mul_f32_e32 v5, v99, v28
	v_mul_f32_e32 v5, v5, v105
	v_lshlrev_b64 v[24:25], 10, v[24:25]
	v_cvt_pk_bf16_f32 v5, v5, s0
	v_lshl_add_u64 v[24:25], v[76:77], 0, v[24:25]
	ds_write_b16 v178, v5 offset:9728
	v_rcp_f32_e32 v24, v9
	v_lshlrev_b32_e32 v5, 16, v85
	v_mul_f32_e32 v5, v9, v5
	v_lshlrev_b32_e32 v106, 16, v122
	v_cvt_pk_bf16_f32 v5, v5, s0
	v_add_f32_e32 v9, v102, v100
	ds_write_b16 v178, v5 offset:9984
	v_mul_f32_e32 v5, v24, v106
	v_mul_f32_e32 v9, 0x3fb8aa3b, v9
	v_cvt_pk_bf16_f32 v5, v5, s0
	v_exp_f32_e32 v9, v9
	v_ashrrev_i32_e32 v21, 31, v20
	ds_write_b16 v178, v5 offset:10240
	v_mul_f32_e32 v5, v99, v24
	v_mul_f32_e32 v5, v5, v106
	v_lshlrev_b64 v[20:21], 10, v[20:21]
	v_cvt_pk_bf16_f32 v5, v5, s0
	v_lshl_add_u64 v[20:21], v[76:77], 0, v[20:21]
	ds_write_b16 v178, v5 offset:10496
	v_lshlrev_b32_e32 v5, 16, v11
	v_rcp_f32_e32 v11, v9
	v_mul_f32_e32 v5, v9, v5
	v_lshlrev_b32_e32 v107, 16, v123
	v_cvt_pk_bf16_f32 v5, v5, s0
	v_add_f32_e32 v9, v100, v104
	ds_write_b16 v178, v5 offset:10752
	v_mul_f32_e32 v5, v11, v107
	v_mul_f32_e32 v9, 0x3fb8aa3b, v9
	v_cvt_pk_bf16_f32 v5, v5, s0
	v_exp_f32_e32 v9, v9
	v_ashrrev_i32_e32 v17, 31, v16
	ds_write_b16 v178, v5 offset:11008
	v_mul_f32_e32 v5, v99, v11
	v_mul_f32_e32 v5, v5, v107
	v_lshlrev_b64 v[16:17], 10, v[16:17]
	v_cvt_pk_bf16_f32 v5, v5, s0
	v_lshl_add_u64 v[16:17], v[76:77], 0, v[16:17]
	ds_write_b16 v178, v5 offset:11264
	v_rcp_f32_e32 v5, v9
	v_lshlrev_b32_e32 v2, 16, v2
	v_mul_f32_e32 v2, v9, v2
	v_lshlrev_b32_e32 v109, 16, v125
	v_cvt_pk_bf16_f32 v2, v2, s0
	ds_write_b16 v178, v2 offset:11520
	v_mul_f32_e32 v2, v5, v109
	v_cvt_pk_bf16_f32 v2, v2, s0
	v_ashrrev_i32_e32 v13, 31, v12
	ds_write_b16 v178, v2 offset:11776
	v_mul_f32_e32 v2, v99, v5
	v_mul_f32_e32 v2, v2, v109
	v_lshlrev_b64 v[12:13], 10, v[12:13]
	v_cvt_pk_bf16_f32 v2, v2, s0
	v_lshl_add_u64 v[12:13], v[76:77], 0, v[12:13]
	ds_write_b16 v178, v2 offset:12032
	s_waitcnt lgkmcnt(0)
	s_barrier
	v_mov_b64_e32 v[194:195], s[94:95]
	v_mov_b64_e32 v[196:197], s[96:97]
	s_mov_b32 s100, 0x5555556
	v_mov_b32_e32 v207, 0
	v_mov_b32_e32 v188, v192
	v_mul_hi_u32 v189, v188, s100
	v_mul_u32_u24_e32 v190, 48, v189
	v_sub_u32_e32 v190, v188, v190
	ds_read_b128 v[184:187], v177
	v_and_b32_e32 v202, 15, v190
	v_lshlrev_b32_e32 v202, 4, v202
	v_bfe_u32 v203, v190, 4, 1
	v_lshl_add_u32 v202, v203, 10, v202
	v_mad_u32_u24 v204, v189, s99, v202
	v_lshlrev_b32_e32 v205, 10, v189
	v_lshl_add_u32 v205, v190, 4, v205
	v_add_u32_e32 v205, 0xfffffe00, v205
	v_cmp_gt_u32_e32 vcc, 32, v190
	s_nop 1
	v_cndmask_b32_e32 v206, v205, v204, vcc
	v_cndmask_b32_e32 v200, v196, v194, vcc
	v_cndmask_b32_e32 v201, v197, v195, vcc
	v_lshl_add_u64 v[200:201], v[206:207], 0, v[200:201]
	s_waitcnt lgkmcnt(0)
	global_store_dwordx4 v[200:201], v[184:187], off
	v_add_u32_e32 v188, 0x200, v192
	v_mul_hi_u32 v189, v188, s100
	v_mul_u32_u24_e32 v190, 48, v189
	v_sub_u32_e32 v190, v188, v190
	ds_read_b128 v[208:211], v177 offset:8192
	v_and_b32_e32 v202, 15, v190
	v_lshlrev_b32_e32 v202, 4, v202
	v_bfe_u32 v203, v190, 4, 1
	v_lshl_add_u32 v202, v203, 10, v202
	v_mad_u32_u24 v204, v189, s99, v202
	v_lshlrev_b32_e32 v205, 10, v189
	v_lshl_add_u32 v205, v190, 4, v205
	v_add_u32_e32 v205, 0xfffffe00, v205
	v_cmp_gt_u32_e32 vcc, 32, v190
	s_nop 1
	v_cndmask_b32_e32 v206, v205, v204, vcc
	v_cndmask_b32_e32 v200, v196, v194, vcc
	v_cndmask_b32_e32 v201, v197, v195, vcc
	v_lshl_add_u64 v[200:201], v[206:207], 0, v[200:201]
	s_waitcnt lgkmcnt(0)
	global_store_dwordx4 v[200:201], v[208:211], off
	v_add_u32_e32 v188, 0x400, v192
	v_mul_hi_u32 v189, v188, s100
	v_mul_u32_u24_e32 v190, 48, v189
	v_sub_u32_e32 v190, v188, v190
	ds_read_b128 v[184:187], v177 offset:16384
	v_and_b32_e32 v202, 15, v190
	v_lshlrev_b32_e32 v202, 4, v202
	v_bfe_u32 v203, v190, 4, 1
	v_lshl_add_u32 v202, v203, 10, v202
	v_mad_u32_u24 v204, v189, s99, v202
	v_lshlrev_b32_e32 v205, 10, v189
	v_lshl_add_u32 v205, v190, 4, v205
	v_add_u32_e32 v205, 0xfffffe00, v205
	v_cmp_gt_u32_e32 vcc, 32, v190
	s_nop 1
	v_cndmask_b32_e32 v206, v205, v204, vcc
	v_cndmask_b32_e32 v200, v196, v194, vcc
	v_cndmask_b32_e32 v201, v197, v195, vcc
	v_lshl_add_u64 v[200:201], v[206:207], 0, v[200:201]
	s_waitcnt lgkmcnt(0)
	global_store_dwordx4 v[200:201], v[184:187], off
	v_add_u32_e32 v188, 0x600, v192
	v_mul_hi_u32 v189, v188, s100
	v_mul_u32_u24_e32 v190, 48, v189
	v_sub_u32_e32 v190, v188, v190
	ds_read_b128 v[208:211], v177 offset:24576
	v_and_b32_e32 v202, 15, v190
	v_lshlrev_b32_e32 v202, 4, v202
	v_bfe_u32 v203, v190, 4, 1
	v_lshl_add_u32 v202, v203, 10, v202
	v_mad_u32_u24 v204, v189, s99, v202
	v_lshlrev_b32_e32 v205, 10, v189
	v_lshl_add_u32 v205, v190, 4, v205
	v_add_u32_e32 v205, 0xfffffe00, v205
	v_cmp_gt_u32_e32 vcc, 32, v190
	s_nop 1
	v_cndmask_b32_e32 v206, v205, v204, vcc
	v_cndmask_b32_e32 v200, v196, v194, vcc
	v_cndmask_b32_e32 v201, v197, v195, vcc
	v_lshl_add_u64 v[200:201], v[206:207], 0, v[200:201]
	s_waitcnt lgkmcnt(0)
	global_store_dwordx4 v[200:201], v[208:211], off
	v_add_u32_e32 v188, 0x800, v192
	v_mul_hi_u32 v189, v188, s100
	v_mul_u32_u24_e32 v190, 48, v189
	v_sub_u32_e32 v190, v188, v190
	ds_read_b128 v[184:187], v177 offset:32768
	v_and_b32_e32 v202, 15, v190
	v_lshlrev_b32_e32 v202, 4, v202
	v_bfe_u32 v203, v190, 4, 1
	v_lshl_add_u32 v202, v203, 10, v202
	v_mad_u32_u24 v204, v189, s99, v202
	v_lshlrev_b32_e32 v205, 10, v189
	v_lshl_add_u32 v205, v190, 4, v205
	v_add_u32_e32 v205, 0xfffffe00, v205
	v_cmp_gt_u32_e32 vcc, 32, v190
	s_nop 1
	v_cndmask_b32_e32 v206, v205, v204, vcc
	v_cndmask_b32_e32 v200, v196, v194, vcc
	v_cndmask_b32_e32 v201, v197, v195, vcc
	v_lshl_add_u64 v[200:201], v[206:207], 0, v[200:201]
	s_waitcnt lgkmcnt(0)
	global_store_dwordx4 v[200:201], v[184:187], off
	v_add_u32_e32 v188, 0xa00, v192
	v_mul_hi_u32 v189, v188, s100
	v_mul_u32_u24_e32 v190, 48, v189
	v_sub_u32_e32 v190, v188, v190
	ds_read_b128 v[208:211], v177 offset:40960
	v_and_b32_e32 v202, 15, v190
	v_lshlrev_b32_e32 v202, 4, v202
	v_bfe_u32 v203, v190, 4, 1
	v_lshl_add_u32 v202, v203, 10, v202
	v_mad_u32_u24 v204, v189, s99, v202
	v_lshlrev_b32_e32 v205, 10, v189
	v_lshl_add_u32 v205, v190, 4, v205
	v_add_u32_e32 v205, 0xfffffe00, v205
	v_cmp_gt_u32_e32 vcc, 32, v190
	s_nop 1
	v_cndmask_b32_e32 v206, v205, v204, vcc
	v_cndmask_b32_e32 v200, v196, v194, vcc
	v_cndmask_b32_e32 v201, v197, v195, vcc
	v_lshl_add_u64 v[200:201], v[206:207], 0, v[200:201]
	s_waitcnt lgkmcnt(0)
	global_store_dwordx4 v[200:201], v[208:211], off
	s_and_saveexec_b64 s[16:17], s[8:9]
	s_cbranch_execz .LBB0_458
	s_lshl_b32 s24, s51, 6
	s_or_b32 s28, s24, s50
	s_ashr_i32 s29, s28, 31
	s_lshl_b64 s[28:29], s[28:29], 11
	s_add_u32 s24, s26, s28
	s_addc_u32 s27, s27, s29
	s_lshl_b32 s26, s49, 2
	s_add_u32 s26, s24, s26
	s_addc_u32 s27, s27, 0
	v_mov_b32_e32 v11, v3
	v_lshl_add_u64 v[12:13], s[26:27], 0, v[10:11]
	v_add_co_u32_e32 v12, vcc, 0x2000000, v12
	s_nop 1
	v_addc_co_u32_e32 v13, vcc, 0, v13, vcc
	global_store_dword v[12:13], v99, off
	s_branch .LBB0_458

.LBB0_470:
	s_nop 0
	v_lshl_add_u32 v54, s11, 6, v47
	v_mad_u64_u32 v[52:53], s[6:7], v54, s9, v[46:47]
	v_cmp_gt_i32_e64 s[6:7], 3, v54
	s_add_i32 s12, s3, s8
	v_add_u32_e32 v57, 0xc0, v54
	v_cndmask_b32_e64 v53, -3, v49, s[6:7]
	v_cmp_gt_i32_e64 s[6:7], 2, v54
	s_waitcnt vmcnt(1)
	ds_write_b128 v52, v[40:43] offset:16384
	v_add_u32_e32 v40, s12, v48
	v_cndmask_b32_e64 v55, -2, v50, s[6:7]
	v_cmp_gt_i32_e64 s[6:7], 1, v54
	v_add_u32_e32 v42, v53, v54
	v_add_u32_e32 v43, v55, v54
	v_cndmask_b32_e64 v56, -1, v51, s[6:7]
	v_cmp_gt_i32_e64 s[6:7], 0, v54
	v_add_u32_e32 v55, v56, v54
	v_add_u32_e32 v58, s12, v47
	v_cndmask_b32_e64 v54, v54, v57, s[6:7]
	v_mad_i64_i32 v[40:41], s[6:7], v40, s10, v[44:45]
	v_mad_u64_u32 v[52:53], s[6:7], v42, s9, v[46:47]
	v_mad_u64_u32 v[56:57], s[6:7], v43, s9, v[46:47]
	global_load_dwordx4 v[40:43], v[40:41], off
	v_mad_u64_u32 v[60:61], s[6:7], v55, s9, v[46:47]
	v_mad_u64_u32 v[64:65], s[6:7], v54, s9, v[46:47]
	v_mad_i64_i32 v[68:69], s[6:7], v58, s10, v[44:45]
	s_waitcnt lgkmcnt(0)
	s_barrier
	ds_read_b128 v[52:55], v52 offset:16384
	ds_read_b128 v[56:59], v56 offset:16384
	ds_read_b128 v[60:63], v60 offset:16384
	ds_read_b128 v[64:67], v64 offset:16384
	s_add_i32 s13, s11, 1
	s_waitcnt lgkmcnt(3)
	v_lshlrev_b32_e32 v70, 16, v52
	v_and_b32_e32 v71, 0xffff0000, v52
	v_lshlrev_b32_e32 v52, 16, v53
	v_and_b32_e32 v53, 0xffff0000, v53
	v_lshlrev_b32_e32 v80, 16, v54
	v_and_b32_e32 v81, 0xffff0000, v54
	v_lshlrev_b32_e32 v54, 16, v55
	v_and_b32_e32 v55, 0xffff0000, v55
	s_waitcnt lgkmcnt(2)
	v_lshlrev_b32_e32 v72, 16, v56
	v_and_b32_e32 v73, 0xffff0000, v56
	v_lshlrev_b32_e32 v56, 16, v57
	v_and_b32_e32 v57, 0xffff0000, v57
	v_lshlrev_b32_e32 v82, 16, v58
	v_and_b32_e32 v83, 0xffff0000, v58
	v_lshlrev_b32_e32 v58, 16, v59
	v_and_b32_e32 v59, 0xffff0000, v59
	v_pk_fma_f32 v[70:71], v[20:21], v[70:71], v[36:37]
	v_pk_fma_f32 v[52:53], v[22:23], v[52:53], v[38:39]
	v_pk_fma_f32 v[80:81], v[0:1], v[80:81], v[16:17]
	v_pk_fma_f32 v[54:55], v[2:3], v[54:55], v[18:19]
	s_waitcnt lgkmcnt(1)
	v_lshlrev_b32_e32 v74, 16, v60
	v_and_b32_e32 v75, 0xffff0000, v60
	v_lshlrev_b32_e32 v60, 16, v61
	v_and_b32_e32 v61, 0xffff0000, v61
	v_lshlrev_b32_e32 v84, 16, v62
	v_and_b32_e32 v85, 0xffff0000, v62
	v_lshlrev_b32_e32 v62, 16, v63
	v_and_b32_e32 v63, 0xffff0000, v63
	v_pk_fma_f32 v[70:71], v[28:29], v[72:73], v[70:71]
	v_pk_fma_f32 v[52:53], v[30:31], v[56:57], v[52:53]
	v_pk_fma_f32 v[56:57], v[8:9], v[82:83], v[80:81]
	v_pk_fma_f32 v[54:55], v[10:11], v[58:59], v[54:55]
	s_waitcnt lgkmcnt(0)
	v_lshlrev_b32_e32 v76, 16, v64
	v_and_b32_e32 v77, 0xffff0000, v64
	v_lshlrev_b32_e32 v64, 16, v65
	v_and_b32_e32 v65, 0xffff0000, v65
	v_lshlrev_b32_e32 v86, 16, v66
	v_and_b32_e32 v87, 0xffff0000, v66
	v_lshlrev_b32_e32 v66, 16, v67
	v_and_b32_e32 v67, 0xffff0000, v67
	v_pk_fma_f32 v[58:59], v[24:25], v[74:75], v[70:71]
	v_pk_fma_f32 v[52:53], v[26:27], v[60:61], v[52:53]
	v_pk_fma_f32 v[56:57], v[4:5], v[84:85], v[56:57]
	v_pk_fma_f32 v[54:55], v[6:7], v[62:63], v[54:55]
	v_pk_fma_f32 v[58:59], v[32:33], v[76:77], v[58:59]
	v_pk_fma_f32 v[52:53], v[34:35], v[64:65], v[52:53]
	v_pk_fma_f32 v[56:57], v[12:13], v[86:87], v[56:57]
	v_pk_fma_f32 v[54:55], v[14:15], v[66:67], v[54:55]
	v_mul_f32_e32 v60, 0xbfb8aa3b, v58
	v_mul_f32_e32 v61, 0xbfb8aa3b, v59
	v_mul_f32_e32 v62, 0xbfb8aa3b, v52
	v_mul_f32_e32 v63, 0xbfb8aa3b, v53
	v_mul_f32_e32 v64, 0xbfb8aa3b, v56
	v_mul_f32_e32 v65, 0xbfb8aa3b, v57
	v_mul_f32_e32 v66, 0xbfb8aa3b, v54
	v_mul_f32_e32 v67, 0xbfb8aa3b, v55
	v_exp_f32_e32 v60, v60
	v_exp_f32_e32 v61, v61
	v_exp_f32_e32 v62, v62
	v_exp_f32_e32 v63, v63
	v_exp_f32_e32 v64, v64
	v_exp_f32_e32 v65, v65
	v_exp_f32_e32 v66, v66
	v_exp_f32_e32 v67, v67
	v_add_f32_e32 v60, 1.0, v60
	v_add_f32_e32 v61, 1.0, v61
	v_add_f32_e32 v62, 1.0, v62
	v_add_f32_e32 v63, 1.0, v63
	v_add_f32_e32 v64, 1.0, v64
	v_add_f32_e32 v65, 1.0, v65
	v_add_f32_e32 v66, 1.0, v66
	v_add_f32_e32 v67, 1.0, v67
	v_rcp_f32_e32 v60, v60
	v_rcp_f32_e32 v61, v61
	v_rcp_f32_e32 v62, v62
	v_rcp_f32_e32 v63, v63
	v_rcp_f32_e32 v64, v64
	v_rcp_f32_e32 v65, v65
	v_rcp_f32_e32 v66, v66
	v_rcp_f32_e32 v67, v67
	s_cmp_lg_u32 s11, 2
	s_cselect_b32 s11, s13, 0
	s_add_i32 s8, s8, 64
	v_pk_mul_f32 v[58:59], v[58:59], v[60:61]
	v_pk_mul_f32 v[60:61], v[52:53], v[62:63]
	v_pk_mul_f32 v[56:57], v[56:57], v[64:65]
	v_pk_mul_f32 v[62:63], v[54:55], v[66:67]
	s_cmpk_lg_i32 s8, 0xfc0
	v_cvt_pk_bf16_f32 v52, v58, v59
	v_cvt_pk_bf16_f32 v53, v60, v61
	v_cvt_pk_bf16_f32 v54, v56, v57
	v_cvt_pk_bf16_f32 v55, v62, v63
	global_store_dwordx4 v[68:69], v[52:55], off
	s_cbranch_scc1 .LBB0_470
	s_or_b32 s6, s3, 0xfc0
	s_movk_i32 s3, 0x90
	v_mad_u32_u24 v56, v47, s3, v46
	s_waitcnt vmcnt(1)
	ds_write_b128 v56, v[40:43] offset:16384
	v_mov_b32_e32 v40, 0xbd
	v_cndmask_b32_e32 v40, -3, v40, vcc
	v_add_u32_e32 v40, v40, v47
	v_mad_i32_i24 v40, v40, s3, v46
	v_mov_b32_e32 v48, 0xbe
	v_cmp_gt_u32_e32 vcc, 16, v192
	s_waitcnt lgkmcnt(0)
	s_barrier
	ds_read_b128 v[40:43], v40 offset:16384
	v_cndmask_b32_e32 v48, -2, v48, vcc
	v_mov_b32_e32 v49, 0xbf
	v_cmp_gt_u32_e32 vcc, 8, v192
	v_add_u32_e32 v48, v48, v47
	v_mad_i32_i24 v48, v48, s3, v46
	v_cndmask_b32_e32 v49, -1, v49, vcc
	v_add_u32_e32 v49, v49, v47
	v_mad_i32_i24 v46, v49, s3, v46
	ds_read_b128 v[48:51], v48 offset:16384
	ds_read_b128 v[52:55], v46 offset:16384
	ds_read_b128 v[56:59], v56 offset:16384
	s_waitcnt lgkmcnt(3)
	v_lshlrev_b32_e32 v60, 16, v40
	v_and_b32_e32 v61, 0xffff0000, v40
	v_pk_fma_f32 v[20:21], v[20:21], v[60:61], v[36:37]
	s_waitcnt lgkmcnt(2)
	v_lshlrev_b32_e32 v36, 16, v48
	v_and_b32_e32 v37, 0xffff0000, v48
	v_pk_fma_f32 v[20:21], v[28:29], v[36:37], v[20:21]
	s_waitcnt lgkmcnt(1)
	v_lshlrev_b32_e32 v28, 16, v52
	v_and_b32_e32 v29, 0xffff0000, v52
	v_pk_fma_f32 v[20:21], v[24:25], v[28:29], v[20:21]
	v_lshlrev_b32_e32 v28, 16, v41
	v_and_b32_e32 v29, 0xffff0000, v41
	v_pk_fma_f32 v[22:23], v[22:23], v[28:29], v[38:39]
	v_lshlrev_b32_e32 v28, 16, v49
	v_and_b32_e32 v29, 0xffff0000, v49
	v_pk_fma_f32 v[22:23], v[30:31], v[28:29], v[22:23]
	v_lshlrev_b32_e32 v28, 16, v53
	v_and_b32_e32 v29, 0xffff0000, v53
	v_pk_fma_f32 v[22:23], v[26:27], v[28:29], v[22:23]
	v_lshlrev_b32_e32 v28, 16, v42
	v_and_b32_e32 v29, 0xffff0000, v42
	v_pk_fma_f32 v[0:1], v[0:1], v[28:29], v[16:17]
	v_lshlrev_b32_e32 v16, 16, v50
	v_and_b32_e32 v17, 0xffff0000, v50
	v_pk_fma_f32 v[0:1], v[8:9], v[16:17], v[0:1]
	v_lshlrev_b32_e32 v8, 16, v54
	v_and_b32_e32 v9, 0xffff0000, v54
	v_pk_fma_f32 v[0:1], v[4:5], v[8:9], v[0:1]
	v_lshlrev_b32_e32 v8, 16, v43
	v_and_b32_e32 v9, 0xffff0000, v43
	v_pk_fma_f32 v[2:3], v[2:3], v[8:9], v[18:19]
	v_lshlrev_b32_e32 v8, 16, v51
	v_and_b32_e32 v9, 0xffff0000, v51
	s_waitcnt lgkmcnt(0)
	v_lshlrev_b32_e32 v4, 16, v58
	v_and_b32_e32 v5, 0xffff0000, v58
	v_pk_fma_f32 v[2:3], v[10:11], v[8:9], v[2:3]
	v_lshlrev_b32_e32 v8, 16, v55
	v_and_b32_e32 v9, 0xffff0000, v55
	v_lshlrev_b32_e32 v24, 16, v56
	v_and_b32_e32 v25, 0xffff0000, v56
	v_lshlrev_b32_e32 v26, 16, v57
	v_and_b32_e32 v27, 0xffff0000, v57
	v_pk_fma_f32 v[0:1], v[12:13], v[4:5], v[0:1]
	v_pk_fma_f32 v[2:3], v[6:7], v[8:9], v[2:3]
	v_lshlrev_b32_e32 v6, 16, v59
	v_and_b32_e32 v7, 0xffff0000, v59
	v_pk_fma_f32 v[20:21], v[32:33], v[24:25], v[20:21]
	v_pk_fma_f32 v[22:23], v[34:35], v[26:27], v[22:23]
	v_mul_f32_e32 v4, 0xbfb8aa3b, v0
	v_mul_f32_e32 v5, 0xbfb8aa3b, v1
	v_pk_fma_f32 v[2:3], v[14:15], v[6:7], v[2:3]
	v_mul_f32_e32 v24, 0xbfb8aa3b, v20
	v_mul_f32_e32 v25, 0xbfb8aa3b, v21
	v_mul_f32_e32 v26, 0xbfb8aa3b, v22
	v_mul_f32_e32 v27, 0xbfb8aa3b, v23
	v_exp_f32_e32 v4, v4
	v_exp_f32_e32 v5, v5
	v_mul_f32_e32 v6, 0xbfb8aa3b, v2
	v_mul_f32_e32 v7, 0xbfb8aa3b, v3
	v_exp_f32_e32 v24, v24
	v_exp_f32_e32 v25, v25
	v_exp_f32_e32 v26, v26
	v_exp_f32_e32 v27, v27
	v_exp_f32_e32 v6, v6
	v_exp_f32_e32 v7, v7
	v_add_f32_e32 v4, 1.0, v4
	v_add_f32_e32 v5, 1.0, v5
	v_add_f32_e32 v24, 1.0, v24
	v_add_f32_e32 v25, 1.0, v25
	v_add_f32_e32 v26, 1.0, v26
	v_add_f32_e32 v27, 1.0, v27
	v_rcp_f32_e32 v4, v4
	v_rcp_f32_e32 v5, v5
	v_add_f32_e32 v6, 1.0, v6
	v_add_f32_e32 v7, 1.0, v7
	v_rcp_f32_e32 v24, v24
	v_rcp_f32_e32 v25, v25
	v_rcp_f32_e32 v26, v26
	v_rcp_f32_e32 v27, v27
	v_rcp_f32_e32 v6, v6
	v_rcp_f32_e32 v7, v7
	v_pk_mul_f32 v[4:5], v[0:1], v[4:5]
	v_pk_mul_f32 v[8:9], v[20:21], v[24:25]
	v_pk_mul_f32 v[10:11], v[22:23], v[26:27]
	v_pk_mul_f32 v[6:7], v[2:3], v[6:7]
	v_cvt_pk_bf16_f32 v2, v4, v5
	v_add_u32_e32 v4, s6, v47
	s_movk_i32 s34, 0x2c00
	v_cvt_pk_bf16_f32 v0, v8, v9
	v_cvt_pk_bf16_f32 v1, v10, v11
	v_cvt_pk_bf16_f32 v3, v6, v7
	v_mad_i64_i32 v[4:5], s[6:7], v4, s34, v[44:45]
	global_store_dwordx4 v[4:5], v[0:3], off
	v_lshlrev_b32_e32 v4, 2, v192
	s_mul_i32 s35, s2, 5
	v_and_b32_e32 v2, 12, v4
	v_and_b32_e32 v0, 0x7f, v192
	s_movk_i32 s6, 0x100
	v_lshlrev_b32_e32 v5, 6, v78
	v_lshlrev_b32_e32 v6, 2, v2
	s_movk_i32 s8, 0x80
	s_movk_i32 s10, 0xff
	s_movk_i32 s12, 0x17f
	s_movk_i32 s14, 0x1ff
	s_mul_i32 s16, s2, 0x280
	s_mov_b32 s3, 0xbfb8aa3b
	v_lshlrev_b32_e32 v1, 4, v79
	v_mov_b32_e32 v3, 0
	v_cmp_gt_u32_e64 s[6:7], s6, v192
	s_mov_b32 s25, 0
	v_add3_u32 v74, 0, v5, v6
	v_lshl_add_u32 v75, v79, 10, 0
	v_add_u32_e32 v76, 0, v4
	v_lshl_add_u32 v77, v0, 2, 0
	v_cmp_gt_u32_e64 s[8:9], s8, v192
	v_cmp_lt_u32_e64 s[10:11], s10, v192
	v_cmp_lt_u32_e64 s[12:13], s12, v192
	v_cmp_lt_u32_e64 s[14:15], s14, v192
	s_addk_i32 s35, 0x440
	s_add_i32 s36, s16, 0x22000
	s_movk_i32 s37, 0x1000
	s_movk_i32 s38, 0x2000
	s_movk_i32 s39, 0x3000
	s_movk_i32 s40, 0x4000
	s_movk_i32 s41, 0x5000
	s_movk_i32 s42, 0x6000
	s_movk_i32 s43, 0x7000
	v_lshlrev_b32_e32 v4, 2, v2
	s_mov_b32 s44, 0x800000
	s_mov_b32 s45, 0x3f317217
	s_mov_b32 s46, 0x7f800000
	s_mov_b32 s47, 0x3d800000
	v_lshlrev_b32_e32 v2, 1, v0
	v_lshlrev_b32_e32 v6, 2, v192
	v_mov_b32_e32 v79, 0x41b17218
	s_mov_b32 s48, 0
	s_barrier
	s_branch .LBB0_473

.LBB0_473:
	s_add_i32 s89, s35, s48
	s_load_dwordx2 s[90:91], s[0:1], 0x100
	s_load_dwordx2 s[92:93], s[0:1], 0xf8
	s_and_b32 s98, s89, 3
	s_lshl_b32 s99, s98, 8
	s_bfe_u32 s98, s89, 0x60002
	s_lshl_b32 s98, s98, 6
	s_ashr_i32 s100, s89, 8
	s_lshl_b32 s100, s100, 12
	s_or_b32 s98, s98, s100
	v_lshrrev_b32_e32 v180, 5, v192
	v_and_b32_e32 v181, 15, v192
	v_lshlrev_b32_e32 v181, 4, v181
	v_bfe_u32 v182, v192, 4, 1
	v_lshl_add_u32 v181, v182, 10, v181
	v_mov_b32_e32 v183, 0
	v_and_b32_e32 v176, 31, v192
	v_lshlrev_b32_e32 v176, 4, v176
	v_lshl_add_u32 v176, v180, 9, v176
	v_add_u32_e32 v176, 0x10000, v176
	v_lshrrev_b32_e32 v177, 7, v192
	v_and_b32_e32 v178, 0x7f, v192
	v_lshlrev_b32_e32 v178, 1, v178
	v_lshl_add_u32 v179, v177, 13, v178
	v_add_u32_e32 v179, 0x10000, v179
	v_mul_u32_u24_e32 v177, 0x3000, v177
	v_add_u32_e32 v178, v177, v178
	v_add_u32_e32 v178, 0x18000, v178
	v_lshlrev_b32_e32 v177, 4, v192
	v_add_u32_e32 v177, 0x18000, v177
	s_waitcnt lgkmcnt(0)
	s_mul_i32 s100, s98, 0x2c00
	s_add_u32 s94, s90, s100
	s_addc_u32 s95, s91, 0
	s_add_u32 s94, s94, s99
	s_addc_u32 s95, s95, 0
	s_lshl_b32 s100, s98, 10
	s_add_u32 s96, s92, s100
	s_addc_u32 s97, s93, 0
	s_add_u32 s96, s96, s99
	s_addc_u32 s97, s97, 0
	s_movk_i32 s99, 0x2c00
	v_mov_b64_e32 v[184:185], s[94:95]
	v_mad_u64_u32 v[184:185], s[100:101], v180, s99, v[184:185]
	v_mov_b32_e32 v182, v181
	v_lshl_add_u64 v[184:185], v[184:185], 0, v[182:183]
	v_mov_b32_e32 v186, 0x2c000
	v_mov_b32_e32 v187, 0
	global_load_dwordx4 v[160:163], v[184:185], off
	v_lshl_add_u64 v[184:185], v[184:185], 0, v[186:187]
	global_load_dwordx4 v[164:167], v[184:185], off
	v_lshl_add_u64 v[184:185], v[184:185], 0, v[186:187]
	global_load_dwordx4 v[168:171], v[184:185], off
	v_lshl_add_u64 v[184:185], v[184:185], 0, v[186:187]
	global_load_dwordx4 v[172:175], v[184:185], off
	s_mov_b64 s[16:17], s[0:1]
	s_load_dwordx2 s[30:31], s[16:17], 0x100
	s_mov_b64 s[26:27], s[0:1]
	s_mov_b64 s[16:17], s[0:1]
	s_load_dwordx2 s[28:29], s[16:17], 0xf8
	s_mov_b64 s[16:17], s[0:1]
	s_mov_b64 s[52:53], s[0:1]
	s_load_dwordx2 s[52:53], s[52:53], 0x38
	s_and_b32 s49, s36, 0x180
	v_or_b32_e32 v5, s49, v0
	v_lshlrev_b32_e32 v8, 2, v5
	v_mov_b32_e32 v9, v3
	s_waitcnt lgkmcnt(0)
	v_lshl_add_u64 v[10:11], s[52:53], 0, v[8:9]
	v_add_co_u32_e32 v12, vcc, s37, v10
	s_add_i32 s24, s35, s48
	s_nop 0
	v_addc_co_u32_e32 v13, vcc, 0, v11, vcc
	v_add_co_u32_e32 v14, vcc, s38, v10
	s_bfe_u32 s50, s24, 0x60002
	s_nop 0
	v_addc_co_u32_e32 v15, vcc, 0, v11, vcc
	v_add_co_u32_e32 v16, vcc, s39, v10
	s_ashr_i32 s51, s24, 8
	s_nop 0
	v_addc_co_u32_e32 v17, vcc, 0, v11, vcc
	v_add_co_u32_e32 v18, vcc, s40, v10
	s_lshl_b32 s24, s51, 12
	s_nop 0
	v_addc_co_u32_e32 v19, vcc, 0, v11, vcc
	v_add_co_u32_e32 v20, vcc, s41, v10
	s_nop 1
	v_addc_co_u32_e32 v21, vcc, 0, v11, vcc
	v_add_co_u32_e32 v22, vcc, s42, v10
	s_nop 1
	v_addc_co_u32_e32 v23, vcc, 0, v11, vcc
	v_add_co_u32_e32 v10, vcc, s43, v10
	global_load_dword v103, v[14:15], off
	global_load_dword v104, v[14:15], off offset:2048
	global_load_dword v100, v[18:19], off offset:-4096
	global_load_dword v72, v[18:19], off
	global_load_dword v95, v[18:19], off offset:2048
	global_load_dword v96, v[22:23], off offset:-4096
	global_load_dword v73, v[22:23], off
	global_load_dword v97, v[22:23], off offset:2048
	v_addc_co_u32_e32 v11, vcc, 0, v11, vcc
	global_load_dword v107, v8, s[52:53]
	global_load_dword v110, v8, s[52:53] offset:2048
	global_load_dword v108, v[14:15], off offset:-4096
	global_load_dword v109, v[12:13], off offset:2048
	global_load_dword v105, v[16:17], off offset:2048
	global_load_dword v101, v[20:21], off offset:2048
	global_load_dword v99, v[10:11], off
	global_load_dword v98, v[10:11], off offset:2048
	s_mov_b64 s[52:53], s[0:1]
	s_load_dwordx2 s[54:55], s[52:53], 0x40
	s_lshl_b32 s52, s50, 6
	s_or_b32 s52, s52, s24
	v_add_u32_e32 v68, s52, v1
	v_mov_b64_e32 v[10:11], s[30:31]
	s_waitcnt lgkmcnt(0)
	global_load_dword v113, v8, s[54:55]
	v_mad_i64_i32 v[8:9], s[30:31], v68, s34, v[10:11]
	s_lshl_b32 s24, s49, 1
	v_lshl_add_u64 v[8:9], v[8:9], 0, s[24:25]
	v_or_b32_e32 v64, 1, v68
	v_lshl_add_u64 v[70:71], v[8:9], 0, v[2:3]
	v_mad_i64_i32 v[8:9], s[30:31], v64, s34, v[10:11]
	v_lshl_add_u64 v[8:9], v[8:9], 0, s[24:25]
	v_or_b32_e32 v60, 2, v68
	v_lshl_add_u64 v[66:67], v[8:9], 0, v[2:3]
	v_mad_i64_i32 v[8:9], s[30:31], v60, s34, v[10:11]
	v_lshl_add_u64 v[8:9], v[8:9], 0, s[24:25]
	v_or_b32_e32 v56, 3, v68
	v_lshl_add_u64 v[62:63], v[8:9], 0, v[2:3]
	v_mad_i64_i32 v[8:9], s[30:31], v56, s34, v[10:11]
	v_lshl_add_u64 v[8:9], v[8:9], 0, s[24:25]
	v_or_b32_e32 v52, 4, v68
	v_lshl_add_u64 v[58:59], v[8:9], 0, v[2:3]
	v_mad_i64_i32 v[8:9], s[30:31], v52, s34, v[10:11]
	v_lshl_add_u64 v[8:9], v[8:9], 0, s[24:25]
	v_or_b32_e32 v48, 5, v68
	v_lshl_add_u64 v[54:55], v[8:9], 0, v[2:3]
	v_mad_i64_i32 v[8:9], s[30:31], v48, s34, v[10:11]
	v_lshl_add_u64 v[8:9], v[8:9], 0, s[24:25]
	v_or_b32_e32 v44, 6, v68
	v_lshl_add_u64 v[50:51], v[8:9], 0, v[2:3]
	v_mad_i64_i32 v[8:9], s[30:31], v44, s34, v[10:11]
	v_lshl_add_u64 v[8:9], v[8:9], 0, s[24:25]
	v_or_b32_e32 v40, 7, v68
	v_lshl_add_u64 v[46:47], v[8:9], 0, v[2:3]
	v_mad_i64_i32 v[8:9], s[30:31], v40, s34, v[10:11]
	v_lshl_add_u64 v[8:9], v[8:9], 0, s[24:25]
	v_or_b32_e32 v36, 8, v68
	v_lshl_add_u64 v[42:43], v[8:9], 0, v[2:3]
	v_mad_i64_i32 v[8:9], s[30:31], v36, s34, v[10:11]
	v_lshl_add_u64 v[8:9], v[8:9], 0, s[24:25]
	v_or_b32_e32 v32, 9, v68
	v_lshl_add_u64 v[38:39], v[8:9], 0, v[2:3]
	v_mad_i64_i32 v[8:9], s[30:31], v32, s34, v[10:11]
	v_lshl_add_u64 v[8:9], v[8:9], 0, s[24:25]
	v_or_b32_e32 v28, 10, v68
	v_lshl_add_u64 v[34:35], v[8:9], 0, v[2:3]
	v_mad_i64_i32 v[8:9], s[30:31], v28, s34, v[10:11]
	v_lshl_add_u64 v[8:9], v[8:9], 0, s[24:25]
	v_or_b32_e32 v24, 11, v68
	v_lshl_add_u64 v[30:31], v[8:9], 0, v[2:3]
	v_mad_i64_i32 v[8:9], s[30:31], v24, s34, v[10:11]
	v_lshl_add_u64 v[8:9], v[8:9], 0, s[24:25]
	v_or_b32_e32 v20, 12, v68
	v_lshl_add_u64 v[26:27], v[8:9], 0, v[2:3]
	v_mad_i64_i32 v[8:9], s[30:31], v20, s34, v[10:11]
	v_lshl_add_u64 v[8:9], v[8:9], 0, s[24:25]
	v_or_b32_e32 v16, 13, v68
	v_lshl_add_u64 v[22:23], v[8:9], 0, v[2:3]
	v_mad_i64_i32 v[8:9], s[30:31], v16, s34, v[10:11]
	v_lshl_add_u64 v[8:9], v[8:9], 0, s[24:25]
	v_or_b32_e32 v12, 14, v68
	v_lshl_add_u64 v[18:19], v[8:9], 0, v[2:3]
	v_mad_i64_i32 v[8:9], s[30:31], v12, s34, v[10:11]
	v_lshl_add_u64 v[8:9], v[8:9], 0, s[24:25]
	v_lshl_add_u64 v[14:15], v[8:9], 0, v[2:3]
	v_or_b32_e32 v8, 15, v68
	v_mad_i64_i32 v[10:11], s[30:31], v8, s34, v[10:11]
	v_lshl_add_u64 v[10:11], v[10:11], 0, s[24:25]
	v_lshl_add_u64 v[10:11], v[10:11], 0, v[2:3]
	s_and_saveexec_b64 s[30:31], s[6:7]
	s_cbranch_execz .LBB0_475
	s_load_dwordx2 s[26:27], s[26:27], 0x100
	v_or_b32_e32 v122, s52, v78
	v_ashrrev_i32_e32 v123, 31, v122
	v_lshlrev_b64 v[122:123], 7, v[122:123]
	v_mov_b32_e32 v5, v3
	s_waitcnt lgkmcnt(0)
	v_lshl_add_u64 v[122:123], s[26:27], 0, v[122:123]
	v_lshl_add_u64 v[122:123], v[122:123], 0, v[4:5]
	v_add_co_u32_e32 v122, vcc, 0x1a200000, v122
	s_nop 1
	v_addc_co_u32_e32 v123, vcc, 0, v123, vcc
	global_load_dwordx4 v[130:133], v[122:123], off
	s_waitcnt vmcnt(0)
	ds_write_b128 v74, v[130:133]
.LBB0_475:
	s_or_b64 exec, exec, s[30:31]
	s_load_dwordx2 s[26:27], s[16:17], 0xf8
	s_waitcnt vmcnt(0)
	ds_write_b128 v176, v[160:163]
	ds_write_b128 v176, v[164:167] offset:8192
	ds_write_b128 v176, v[168:171] offset:16384
	ds_write_b128 v176, v[172:175] offset:24576
	s_waitcnt lgkmcnt(0)
	s_barrier
	ds_read_u16 v94, v179
	ds_read_u16 v106, v179 offset:256
	ds_read_u16 v93, v179 offset:512
	ds_read_u16 v111, v179 offset:768
	ds_read_u16 v92, v179 offset:1024
	ds_read_u16 v114, v179 offset:1280
	ds_read_u16 v90, v179 offset:1536
	ds_read_u16 v115, v179 offset:1792
	ds_read_u16 v91, v179 offset:2048
	ds_read_u16 v116, v179 offset:2304
	ds_read_u16 v89, v179 offset:2560
	ds_read_u16 v129, v179 offset:2816
	ds_read_u16 v88, v179 offset:3072
	ds_read_u16 v128, v179 offset:3328
	ds_read_u16 v86, v179 offset:3584
	ds_read_u16 v102, v179 offset:3840
	ds_read_u16 v87, v179 offset:4096
	ds_read_u16 v112, v179 offset:4352
	ds_read_u16 v85, v179 offset:4608
	ds_read_u16 v127, v179 offset:4864
	ds_read_u16 v84, v179 offset:5120
	ds_read_u16 v125, v179 offset:5376
	ds_read_u16 v82, v179 offset:5632
	ds_read_u16 v126, v179 offset:5888
	ds_read_u16 v83, v179 offset:6144
	ds_read_u16 v118, v179 offset:6400
	ds_read_u16 v81, v179 offset:6656
	ds_read_u16 v119, v179 offset:6912
	ds_read_u16 v80, v179 offset:7168
	ds_read_u16 v120, v179 offset:7424
	ds_read_u16 v7, v179 offset:7680
	ds_read_u16 v121, v179 offset:7936
	s_waitcnt lgkmcnt(0)
	ds_read_b128 v[130:133], v75
	ds_read_b128 v[134:137], v75 offset:16
	ds_read_b128 v[138:141], v75 offset:32
	ds_read_b128 v[142:145], v75 offset:48
	s_waitcnt vmcnt(30)
	v_lshlrev_b32_e32 v124, 16, v106
	s_waitcnt vmcnt(28)
	v_lshlrev_b32_e32 v123, 16, v111
	s_waitcnt lgkmcnt(2)
	v_mul_f32_e32 v106, v104, v135
	v_mul_f32_e32 v5, v110, v131
	v_fmac_f32_e32 v5, v107, v130
	v_fmac_f32_e32 v5, v108, v132
	v_fmac_f32_e32 v106, v103, v134
	v_fmac_f32_e32 v5, v109, v133
	v_fmac_f32_e32 v106, v100, v136
	v_add_f32_e32 v5, v113, v5
	v_fmac_f32_e32 v106, v105, v137
	v_add_f32_e32 v5, v5, v106
	s_waitcnt lgkmcnt(1)
	v_mul_f32_e32 v106, v95, v139
	v_fmac_f32_e32 v106, v72, v138
	v_fmac_f32_e32 v106, v96, v140
	v_fmac_f32_e32 v106, v101, v141
	v_add_f32_e32 v5, v5, v106
	s_waitcnt lgkmcnt(0)
	v_mul_f32_e32 v106, v97, v143
	v_fmac_f32_e32 v106, v73, v142
	v_fmac_f32_e32 v106, v99, v144
	v_fmac_f32_e32 v106, v98, v145
	s_waitcnt vmcnt(18)
	v_lshlrev_b32_e32 v111, 16, v128
	v_add_f32_e32 v128, v5, v106
	v_mul_f32_e64 v5, |v128|, s3
	v_exp_f32_e32 v5, v5
	v_lshlrev_b32_e32 v117, 16, v115
	s_waitcnt vmcnt(16)
	v_lshlrev_b32_e32 v115, 16, v102
	v_lshlrev_b32_e32 v122, 16, v114
	v_add_f32_e32 v5, 1.0, v5
	v_cmp_gt_f32_e32 vcc, s44, v5
	v_lshlrev_b32_e32 v114, 16, v129
	s_waitcnt vmcnt(12)
	v_lshlrev_b32_e32 v106, 16, v127
	v_cndmask_b32_e64 v102, 0, 32, vcc
	v_ldexp_f32 v5, v5, v102
	v_log_f32_e32 v134, v5
	s_waitcnt vmcnt(10)
	v_lshlrev_b32_e32 v102, 16, v125
	s_waitcnt vmcnt(8)
	v_lshlrev_b32_e32 v5, 16, v126
	v_min_f32_e32 v125, 0, v128
	ds_read_b128 v[126:129], v75 offset:64
	v_mul_f32_e32 v130, 0x3f317217, v134
	v_fma_f32 v135, v134, s45, -v130
	ds_read_b128 v[130:133], v75 offset:80
	v_fmac_f32_e32 v135, 0x3377d1cf, v134
	s_waitcnt lgkmcnt(1)
	v_mul_f32_e32 v127, v110, v127
	v_fmac_f32_e32 v127, v107, v126
	v_fmac_f32_e32 v127, v108, v128
	v_fmac_f32_e32 v127, v109, v129
	v_add_f32_e32 v136, v113, v127
	s_waitcnt lgkmcnt(0)
	v_mul_f32_e32 v131, v104, v131
	ds_read_b128 v[126:129], v75 offset:96
	v_fmac_f32_e32 v131, v103, v130
	v_fmac_f32_e32 v131, v100, v132
	v_fmac_f32_e32 v131, v105, v133
	v_add_f32_e32 v136, v136, v131
	ds_read_b128 v[130:133], v75 offset:112
	s_waitcnt lgkmcnt(1)
	v_mul_f32_e32 v127, v95, v127
	v_fmac_f32_e32 v127, v72, v126
	v_fmac_f32_e32 v127, v96, v128
	v_fmac_f32_e32 v127, v101, v129
	v_add_f32_e32 v126, v136, v127
	s_waitcnt lgkmcnt(0)
	v_mul_f32_e32 v127, v97, v131
	v_fmac_f32_e32 v127, v73, v130
	v_fmac_f32_e32 v127, v99, v132
	v_fmac_f32_e32 v127, v98, v133
	v_add_f32_e32 v126, v126, v127
	v_mul_f32_e64 v127, |v126|, s3
	v_exp_f32_e32 v127, v127
	v_fmac_f32_e32 v135, 0x3f317217, v134
	v_cmp_lt_f32_e64 s[16:17], |v134|, s46
	v_cndmask_b32_e32 v129, 0, v79, vcc
	v_add_f32_e32 v127, 1.0, v127
	v_cndmask_b32_e64 v128, v134, v135, s[16:17]
	v_cmp_gt_f32_e32 vcc, s44, v127
	v_sub_f32_e32 v128, v128, v129
	v_sub_f32_e32 v125, v125, v128
	v_cndmask_b32_e64 v129, 0, 32, vcc
	v_ldexp_f32 v127, v127, v129
	v_log_f32_e32 v134, v127
	v_min_f32_e32 v135, 0, v126
	ds_read_b128 v[126:129], v75 offset:128
	v_fma_f32 v125, v125, s47, 0
	v_mul_f32_e32 v130, 0x3f317217, v134
	v_fma_f32 v136, v134, s45, -v130
	ds_read_b128 v[130:133], v75 offset:144
	s_waitcnt lgkmcnt(1)
	v_mul_f32_e32 v127, v110, v127
	v_fmac_f32_e32 v127, v107, v126
	v_fmac_f32_e32 v127, v108, v128
	v_fmac_f32_e32 v127, v109, v129
	v_add_f32_e32 v137, v113, v127
	s_waitcnt lgkmcnt(0)
	v_mul_f32_e32 v131, v104, v131
	ds_read_b128 v[126:129], v75 offset:160
	v_fmac_f32_e32 v131, v103, v130
	v_fmac_f32_e32 v131, v100, v132
	v_fmac_f32_e32 v131, v105, v133
	v_add_f32_e32 v137, v137, v131
	ds_read_b128 v[130:133], v75 offset:176
	s_waitcnt lgkmcnt(1)
	v_mul_f32_e32 v127, v95, v127
	v_fmac_f32_e32 v127, v72, v126
	v_fmac_f32_e32 v127, v96, v128
	v_fmac_f32_e32 v127, v101, v129
	v_add_f32_e32 v126, v137, v127
	s_waitcnt lgkmcnt(0)
	v_mul_f32_e32 v127, v97, v131
	v_fmac_f32_e32 v127, v73, v130
	v_fmac_f32_e32 v127, v99, v132
	v_fmac_f32_e32 v127, v98, v133
	v_add_f32_e32 v127, v126, v127
	v_mul_f32_e64 v126, |v127|, s3
	v_exp_f32_e32 v126, v126
	v_fmac_f32_e32 v136, 0x3377d1cf, v134
	v_fmac_f32_e32 v136, 0x3f317217, v134
	v_cmp_lt_f32_e64 s[16:17], |v134|, s46
	v_add_f32_e32 v126, 1.0, v126
	v_cndmask_b32_e32 v129, 0, v79, vcc
	v_cndmask_b32_e64 v128, v134, v136, s[16:17]
	v_cmp_gt_f32_e32 vcc, s44, v126
	v_sub_f32_e32 v128, v128, v129
	v_min_f32_e32 v127, 0, v127
	v_cndmask_b32_e64 v129, 0, 32, vcc
	v_ldexp_f32 v126, v126, v129
	v_log_f32_e32 v136, v126
	v_sub_f32_e32 v126, v135, v128
	ds_read_b128 v[128:131], v75 offset:192
	v_fmamk_f32 v126, v126, 0x3d800000, v125
	v_mul_f32_e32 v132, 0x3f317217, v136
	v_fma_f32 v137, v136, s45, -v132
	ds_read_b128 v[132:135], v75 offset:208
	s_waitcnt lgkmcnt(1)
	v_mul_f32_e32 v129, v110, v129
	v_fmac_f32_e32 v129, v107, v128
	v_fmac_f32_e32 v129, v108, v130
	v_fmac_f32_e32 v129, v109, v131
	v_add_f32_e32 v138, v113, v129
	s_waitcnt lgkmcnt(0)
	v_mul_f32_e32 v133, v104, v133
	ds_read_b128 v[128:131], v75 offset:224
	v_fmac_f32_e32 v133, v103, v132
	v_fmac_f32_e32 v133, v100, v134
	v_fmac_f32_e32 v133, v105, v135
	v_add_f32_e32 v138, v138, v133
	ds_read_b128 v[132:135], v75 offset:240
	s_waitcnt lgkmcnt(1)
	v_mul_f32_e32 v129, v95, v129
	v_fmac_f32_e32 v129, v72, v128
	v_fmac_f32_e32 v129, v96, v130
	v_fmac_f32_e32 v129, v101, v131
	v_add_f32_e32 v128, v138, v129
	s_waitcnt lgkmcnt(0)
	v_mul_f32_e32 v129, v97, v133
	v_fmac_f32_e32 v129, v73, v132
	v_fmac_f32_e32 v129, v99, v134
	v_fmac_f32_e32 v129, v98, v135
	v_add_f32_e32 v128, v128, v129
	v_mul_f32_e64 v129, |v128|, s3
	v_exp_f32_e32 v129, v129
	v_fmac_f32_e32 v137, 0x3377d1cf, v136
	v_fmac_f32_e32 v137, 0x3f317217, v136
	v_cmp_lt_f32_e64 s[16:17], |v136|, s46
	v_add_f32_e32 v129, 1.0, v129
	v_cndmask_b32_e32 v131, 0, v79, vcc
	v_cndmask_b32_e64 v130, v136, v137, s[16:17]
	v_cmp_gt_f32_e32 vcc, s44, v129
	v_sub_f32_e32 v130, v130, v131
	v_sub_f32_e32 v127, v127, v130
	v_cndmask_b32_e64 v131, 0, 32, vcc
	v_ldexp_f32 v129, v129, v131
	v_log_f32_e32 v136, v129
	v_min_f32_e32 v137, 0, v128
	ds_read_b128 v[128:131], v75 offset:256
	v_fmamk_f32 v127, v127, 0x3d800000, v126
	v_mul_f32_e32 v132, 0x3f317217, v136
	v_fma_f32 v138, v136, s45, -v132
	ds_read_b128 v[132:135], v75 offset:272
	s_waitcnt lgkmcnt(1)
	v_mul_f32_e32 v129, v110, v129
	v_fmac_f32_e32 v129, v107, v128
	v_fmac_f32_e32 v129, v108, v130
	v_fmac_f32_e32 v129, v109, v131
	v_add_f32_e32 v139, v113, v129
	s_waitcnt lgkmcnt(0)
	v_mul_f32_e32 v133, v104, v133
	ds_read_b128 v[128:131], v75 offset:288
	v_fmac_f32_e32 v133, v103, v132
	v_fmac_f32_e32 v133, v100, v134
	v_fmac_f32_e32 v133, v105, v135
	v_add_f32_e32 v139, v139, v133
	ds_read_b128 v[132:135], v75 offset:304
	s_waitcnt lgkmcnt(1)
	v_mul_f32_e32 v129, v95, v129
	v_fmac_f32_e32 v129, v72, v128
	v_fmac_f32_e32 v129, v96, v130
	v_fmac_f32_e32 v129, v101, v131
	v_add_f32_e32 v128, v139, v129
	s_waitcnt lgkmcnt(0)
	v_mul_f32_e32 v129, v97, v133
	v_fmac_f32_e32 v129, v73, v132
	v_fmac_f32_e32 v129, v99, v134
	v_fmac_f32_e32 v129, v98, v135
	v_add_f32_e32 v129, v128, v129
	v_mul_f32_e64 v128, |v129|, s3
	v_exp_f32_e32 v128, v128
	v_fmac_f32_e32 v138, 0x3377d1cf, v136
	v_fmac_f32_e32 v138, 0x3f317217, v136
	v_cmp_lt_f32_e64 s[16:17], |v136|, s46
	v_add_f32_e32 v128, 1.0, v128
	v_cndmask_b32_e32 v131, 0, v79, vcc
	v_cndmask_b32_e64 v130, v136, v138, s[16:17]
	v_cmp_gt_f32_e32 vcc, s44, v128
	v_sub_f32_e32 v130, v130, v131
	v_min_f32_e32 v129, 0, v129
	v_cndmask_b32_e64 v131, 0, 32, vcc
	v_ldexp_f32 v128, v128, v131
	v_log_f32_e32 v138, v128
	v_sub_f32_e32 v128, v137, v130
	ds_read_b128 v[130:133], v75 offset:320
	v_fmamk_f32 v128, v128, 0x3d800000, v127
	v_mul_f32_e32 v134, 0x3f317217, v138
	v_fma_f32 v139, v138, s45, -v134
	ds_read_b128 v[134:137], v75 offset:336
	s_waitcnt lgkmcnt(1)
	v_mul_f32_e32 v131, v110, v131
	v_fmac_f32_e32 v131, v107, v130
	v_fmac_f32_e32 v131, v108, v132
	v_fmac_f32_e32 v131, v109, v133
	v_add_f32_e32 v140, v113, v131
	s_waitcnt lgkmcnt(0)
	v_mul_f32_e32 v135, v104, v135
	ds_read_b128 v[130:133], v75 offset:352
	v_fmac_f32_e32 v135, v103, v134
	v_fmac_f32_e32 v135, v100, v136
	v_fmac_f32_e32 v135, v105, v137
	v_add_f32_e32 v140, v140, v135
	ds_read_b128 v[134:137], v75 offset:368
	s_waitcnt lgkmcnt(1)
	v_mul_f32_e32 v131, v95, v131
	v_fmac_f32_e32 v131, v72, v130
	v_fmac_f32_e32 v131, v96, v132
	v_fmac_f32_e32 v131, v101, v133
	v_add_f32_e32 v130, v140, v131
	s_waitcnt lgkmcnt(0)
	v_mul_f32_e32 v131, v97, v135
	v_fmac_f32_e32 v131, v73, v134
	v_fmac_f32_e32 v131, v99, v136
	v_fmac_f32_e32 v131, v98, v137
	v_add_f32_e32 v130, v130, v131
	v_mul_f32_e64 v131, |v130|, s3
	v_exp_f32_e32 v131, v131
	v_fmac_f32_e32 v139, 0x3377d1cf, v138
	v_fmac_f32_e32 v139, 0x3f317217, v138
	v_cmp_lt_f32_e64 s[16:17], |v138|, s46
	v_add_f32_e32 v131, 1.0, v131
	v_cndmask_b32_e32 v133, 0, v79, vcc
	v_cndmask_b32_e64 v132, v138, v139, s[16:17]
	v_cmp_gt_f32_e32 vcc, s44, v131
	v_sub_f32_e32 v132, v132, v133
	v_sub_f32_e32 v129, v129, v132
	v_cndmask_b32_e64 v133, 0, 32, vcc
	v_ldexp_f32 v131, v131, v133
	v_log_f32_e32 v138, v131
	v_min_f32_e32 v139, 0, v130
	ds_read_b128 v[130:133], v75 offset:384
	v_fmamk_f32 v129, v129, 0x3d800000, v128
	v_mul_f32_e32 v134, 0x3f317217, v138
	v_fma_f32 v140, v138, s45, -v134
	ds_read_b128 v[134:137], v75 offset:400
	s_waitcnt lgkmcnt(1)
	v_mul_f32_e32 v131, v110, v131
	v_fmac_f32_e32 v131, v107, v130
	v_fmac_f32_e32 v131, v108, v132
	v_fmac_f32_e32 v131, v109, v133
	v_add_f32_e32 v141, v113, v131
	s_waitcnt lgkmcnt(0)
	v_mul_f32_e32 v135, v104, v135
	ds_read_b128 v[130:133], v75 offset:416
	v_fmac_f32_e32 v135, v103, v134
	v_fmac_f32_e32 v135, v100, v136
	v_fmac_f32_e32 v135, v105, v137
	v_add_f32_e32 v141, v141, v135
	ds_read_b128 v[134:137], v75 offset:432
	s_waitcnt lgkmcnt(1)
	v_mul_f32_e32 v131, v95, v131
	v_fmac_f32_e32 v131, v72, v130
	v_fmac_f32_e32 v131, v96, v132
	v_fmac_f32_e32 v131, v101, v133
	v_add_f32_e32 v130, v141, v131
	s_waitcnt lgkmcnt(0)
	v_mul_f32_e32 v131, v97, v135
	v_fmac_f32_e32 v131, v73, v134
	v_fmac_f32_e32 v131, v99, v136
	v_fmac_f32_e32 v131, v98, v137
	v_add_f32_e32 v131, v130, v131
	v_mul_f32_e64 v130, |v131|, s3
	v_exp_f32_e32 v130, v130
	v_fmac_f32_e32 v140, 0x3377d1cf, v138
	v_fmac_f32_e32 v140, 0x3f317217, v138
	v_cmp_lt_f32_e64 s[16:17], |v138|, s46
	v_add_f32_e32 v130, 1.0, v130
	v_cndmask_b32_e32 v133, 0, v79, vcc
	v_cndmask_b32_e64 v132, v138, v140, s[16:17]
	v_cmp_gt_f32_e32 vcc, s44, v130
	v_sub_f32_e32 v132, v132, v133
	v_min_f32_e32 v131, 0, v131
	v_cndmask_b32_e64 v133, 0, 32, vcc
	v_ldexp_f32 v130, v130, v133
	v_log_f32_e32 v140, v130
	v_sub_f32_e32 v130, v139, v132
	ds_read_b128 v[132:135], v75 offset:448
	v_fmamk_f32 v130, v130, 0x3d800000, v129
	v_mul_f32_e32 v136, 0x3f317217, v140
	v_fma_f32 v141, v140, s45, -v136
	ds_read_b128 v[136:139], v75 offset:464
	s_waitcnt lgkmcnt(1)
	v_mul_f32_e32 v133, v110, v133
	v_fmac_f32_e32 v133, v107, v132
	v_fmac_f32_e32 v133, v108, v134
	v_fmac_f32_e32 v133, v109, v135
	v_add_f32_e32 v142, v113, v133
	s_waitcnt lgkmcnt(0)
	v_mul_f32_e32 v137, v104, v137
	ds_read_b128 v[132:135], v75 offset:480
	v_fmac_f32_e32 v137, v103, v136
	v_fmac_f32_e32 v137, v100, v138
	v_fmac_f32_e32 v137, v105, v139
	v_add_f32_e32 v142, v142, v137
	ds_read_b128 v[136:139], v75 offset:496
	s_waitcnt lgkmcnt(1)
	v_mul_f32_e32 v133, v95, v133
	v_fmac_f32_e32 v133, v72, v132
	v_fmac_f32_e32 v133, v96, v134
	v_fmac_f32_e32 v133, v101, v135
	v_add_f32_e32 v132, v142, v133
	s_waitcnt lgkmcnt(0)
	v_mul_f32_e32 v133, v97, v137
	v_fmac_f32_e32 v133, v73, v136
	v_fmac_f32_e32 v133, v99, v138
	v_fmac_f32_e32 v133, v98, v139
	v_add_f32_e32 v132, v132, v133
	v_mul_f32_e64 v133, |v132|, s3
	v_exp_f32_e32 v133, v133
	v_fmac_f32_e32 v141, 0x3377d1cf, v140
	v_fmac_f32_e32 v141, 0x3f317217, v140
	v_cmp_lt_f32_e64 s[16:17], |v140|, s46
	v_add_f32_e32 v133, 1.0, v133
	v_cndmask_b32_e32 v135, 0, v79, vcc
	v_cndmask_b32_e64 v134, v140, v141, s[16:17]
	v_cmp_gt_f32_e32 vcc, s44, v133
	v_sub_f32_e32 v134, v134, v135
	v_sub_f32_e32 v131, v131, v134
	v_cndmask_b32_e64 v135, 0, 32, vcc
	v_ldexp_f32 v133, v133, v135
	v_log_f32_e32 v140, v133
	v_min_f32_e32 v141, 0, v132
	ds_read_b128 v[132:135], v75 offset:512
	v_fmamk_f32 v131, v131, 0x3d800000, v130
	v_mul_f32_e32 v136, 0x3f317217, v140
	v_fma_f32 v142, v140, s45, -v136
	ds_read_b128 v[136:139], v75 offset:528
	s_waitcnt lgkmcnt(1)
	v_mul_f32_e32 v133, v110, v133
	v_fmac_f32_e32 v133, v107, v132
	v_fmac_f32_e32 v133, v108, v134
	v_fmac_f32_e32 v133, v109, v135
	v_add_f32_e32 v143, v113, v133
	s_waitcnt lgkmcnt(0)
	v_mul_f32_e32 v137, v104, v137
	ds_read_b128 v[132:135], v75 offset:544
	v_fmac_f32_e32 v137, v103, v136
	v_fmac_f32_e32 v137, v100, v138
	v_fmac_f32_e32 v137, v105, v139
	v_add_f32_e32 v143, v143, v137
	ds_read_b128 v[136:139], v75 offset:560
	s_waitcnt lgkmcnt(1)
	v_mul_f32_e32 v133, v95, v133
	v_fmac_f32_e32 v133, v72, v132
	v_fmac_f32_e32 v133, v96, v134
	v_fmac_f32_e32 v133, v101, v135
	v_add_f32_e32 v132, v143, v133
	s_waitcnt lgkmcnt(0)
	v_mul_f32_e32 v133, v97, v137
	v_fmac_f32_e32 v133, v73, v136
	v_fmac_f32_e32 v133, v99, v138
	v_fmac_f32_e32 v133, v98, v139
	v_add_f32_e32 v133, v132, v133
	v_mul_f32_e64 v132, |v133|, s3
	v_exp_f32_e32 v132, v132
	v_fmac_f32_e32 v142, 0x3377d1cf, v140
	v_fmac_f32_e32 v142, 0x3f317217, v140
	v_cmp_lt_f32_e64 s[16:17], |v140|, s46
	v_add_f32_e32 v132, 1.0, v132
	v_cndmask_b32_e32 v135, 0, v79, vcc
	v_cndmask_b32_e64 v134, v140, v142, s[16:17]
	v_cmp_gt_f32_e32 vcc, s44, v132
	v_sub_f32_e32 v134, v134, v135
	v_min_f32_e32 v133, 0, v133
	v_cndmask_b32_e64 v135, 0, 32, vcc
	v_ldexp_f32 v132, v132, v135
	v_log_f32_e32 v142, v132
	v_sub_f32_e32 v132, v141, v134
	ds_read_b128 v[134:137], v75 offset:576
	v_fmamk_f32 v132, v132, 0x3d800000, v131
	v_mul_f32_e32 v138, 0x3f317217, v142
	v_fma_f32 v143, v142, s45, -v138
	ds_read_b128 v[138:141], v75 offset:592
	s_waitcnt lgkmcnt(1)
	v_mul_f32_e32 v135, v110, v135
	v_fmac_f32_e32 v135, v107, v134
	v_fmac_f32_e32 v135, v108, v136
	v_fmac_f32_e32 v135, v109, v137
	v_add_f32_e32 v144, v113, v135
	s_waitcnt lgkmcnt(0)
	v_mul_f32_e32 v139, v104, v139
	ds_read_b128 v[134:137], v75 offset:608
	v_fmac_f32_e32 v139, v103, v138
	v_fmac_f32_e32 v139, v100, v140
	v_fmac_f32_e32 v139, v105, v141
	v_add_f32_e32 v144, v144, v139
	ds_read_b128 v[138:141], v75 offset:624
	s_waitcnt lgkmcnt(1)
	v_mul_f32_e32 v135, v95, v135
	v_fmac_f32_e32 v135, v72, v134
	v_fmac_f32_e32 v135, v96, v136
	v_fmac_f32_e32 v135, v101, v137
	v_add_f32_e32 v134, v144, v135
	s_waitcnt lgkmcnt(0)
	v_mul_f32_e32 v135, v97, v139
	v_fmac_f32_e32 v135, v73, v138
	v_fmac_f32_e32 v135, v99, v140
	v_fmac_f32_e32 v135, v98, v141
	v_add_f32_e32 v134, v134, v135
	v_mul_f32_e64 v135, |v134|, s3
	v_exp_f32_e32 v135, v135
	v_fmac_f32_e32 v143, 0x3377d1cf, v142
	v_fmac_f32_e32 v143, 0x3f317217, v142
	v_cmp_lt_f32_e64 s[16:17], |v142|, s46
	v_add_f32_e32 v135, 1.0, v135
	v_cndmask_b32_e32 v137, 0, v79, vcc
	v_cndmask_b32_e64 v136, v142, v143, s[16:17]
	v_cmp_gt_f32_e32 vcc, s44, v135
	v_sub_f32_e32 v136, v136, v137
	v_sub_f32_e32 v133, v133, v136
	v_cndmask_b32_e64 v137, 0, 32, vcc
	v_ldexp_f32 v135, v135, v137
	v_log_f32_e32 v142, v135
	v_min_f32_e32 v143, 0, v134
	ds_read_b128 v[134:137], v75 offset:640
	v_fmamk_f32 v133, v133, 0x3d800000, v132
	v_mul_f32_e32 v138, 0x3f317217, v142
	v_fma_f32 v144, v142, s45, -v138
	ds_read_b128 v[138:141], v75 offset:656
	s_waitcnt lgkmcnt(1)
	v_mul_f32_e32 v135, v110, v135
	v_fmac_f32_e32 v135, v107, v134
	v_fmac_f32_e32 v135, v108, v136
	v_fmac_f32_e32 v135, v109, v137
	v_add_f32_e32 v145, v113, v135
	s_waitcnt lgkmcnt(0)
	v_mul_f32_e32 v139, v104, v139
	ds_read_b128 v[134:137], v75 offset:672
	v_fmac_f32_e32 v139, v103, v138
	v_fmac_f32_e32 v139, v100, v140
	v_fmac_f32_e32 v139, v105, v141
	v_add_f32_e32 v145, v145, v139
	ds_read_b128 v[138:141], v75 offset:688
	s_waitcnt lgkmcnt(1)
	v_mul_f32_e32 v135, v95, v135
	v_fmac_f32_e32 v135, v72, v134
	v_fmac_f32_e32 v135, v96, v136
	v_fmac_f32_e32 v135, v101, v137
	v_add_f32_e32 v134, v145, v135
	s_waitcnt lgkmcnt(0)
	v_mul_f32_e32 v135, v97, v139
	v_fmac_f32_e32 v135, v73, v138
	v_fmac_f32_e32 v135, v99, v140
	v_fmac_f32_e32 v135, v98, v141
	v_add_f32_e32 v135, v134, v135
	v_mul_f32_e64 v134, |v135|, s3
	v_exp_f32_e32 v134, v134
	v_fmac_f32_e32 v144, 0x3377d1cf, v142
	v_fmac_f32_e32 v144, 0x3f317217, v142
	v_cmp_lt_f32_e64 s[16:17], |v142|, s46
	v_add_f32_e32 v134, 1.0, v134
	v_cndmask_b32_e32 v137, 0, v79, vcc
	v_cndmask_b32_e64 v136, v142, v144, s[16:17]
	v_cmp_gt_f32_e32 vcc, s44, v134
	v_sub_f32_e32 v136, v136, v137
	v_min_f32_e32 v135, 0, v135
	v_cndmask_b32_e64 v137, 0, 32, vcc
	v_ldexp_f32 v134, v134, v137
	v_log_f32_e32 v144, v134
	v_sub_f32_e32 v134, v143, v136
	ds_read_b128 v[136:139], v75 offset:704
	v_fmamk_f32 v134, v134, 0x3d800000, v133
	v_mul_f32_e32 v140, 0x3f317217, v144
	v_fma_f32 v145, v144, s45, -v140
	ds_read_b128 v[140:143], v75 offset:720
	s_waitcnt lgkmcnt(1)
	v_mul_f32_e32 v137, v110, v137
	v_fmac_f32_e32 v137, v107, v136
	v_fmac_f32_e32 v137, v108, v138
	v_fmac_f32_e32 v137, v109, v139
	v_add_f32_e32 v146, v113, v137
	s_waitcnt lgkmcnt(0)
	v_mul_f32_e32 v141, v104, v141
	ds_read_b128 v[136:139], v75 offset:736
	v_fmac_f32_e32 v141, v103, v140
	v_fmac_f32_e32 v141, v100, v142
	v_fmac_f32_e32 v141, v105, v143
	v_add_f32_e32 v146, v146, v141
	ds_read_b128 v[140:143], v75 offset:752
	s_waitcnt lgkmcnt(1)
	v_mul_f32_e32 v137, v95, v137
	v_fmac_f32_e32 v137, v72, v136
	v_fmac_f32_e32 v137, v96, v138
	v_fmac_f32_e32 v137, v101, v139
	v_add_f32_e32 v136, v146, v137
	s_waitcnt lgkmcnt(0)
	v_mul_f32_e32 v137, v97, v141
	v_fmac_f32_e32 v137, v73, v140
	v_fmac_f32_e32 v137, v99, v142
	v_fmac_f32_e32 v137, v98, v143
	v_add_f32_e32 v136, v136, v137
	v_mul_f32_e64 v137, |v136|, s3
	v_exp_f32_e32 v137, v137
	v_fmac_f32_e32 v145, 0x3377d1cf, v144
	v_fmac_f32_e32 v145, 0x3f317217, v144
	v_cmp_lt_f32_e64 s[16:17], |v144|, s46
	v_add_f32_e32 v137, 1.0, v137
	v_cndmask_b32_e32 v139, 0, v79, vcc
	v_cndmask_b32_e64 v138, v144, v145, s[16:17]
	v_cmp_gt_f32_e32 vcc, s44, v137
	v_sub_f32_e32 v138, v138, v139
	v_sub_f32_e32 v135, v135, v138
	v_cndmask_b32_e64 v139, 0, 32, vcc
	v_ldexp_f32 v137, v137, v139
	v_log_f32_e32 v144, v137
	v_min_f32_e32 v145, 0, v136
	ds_read_b128 v[136:139], v75 offset:768
	v_fmamk_f32 v135, v135, 0x3d800000, v134
	v_mul_f32_e32 v140, 0x3f317217, v144
	v_fma_f32 v146, v144, s45, -v140
	ds_read_b128 v[140:143], v75 offset:784
	s_waitcnt lgkmcnt(1)
	v_mul_f32_e32 v137, v110, v137
	v_fmac_f32_e32 v137, v107, v136
	v_fmac_f32_e32 v137, v108, v138
	v_fmac_f32_e32 v137, v109, v139
	v_add_f32_e32 v147, v113, v137
	s_waitcnt lgkmcnt(0)
	v_mul_f32_e32 v141, v104, v141
	ds_read_b128 v[136:139], v75 offset:800
	v_fmac_f32_e32 v141, v103, v140
	v_fmac_f32_e32 v141, v100, v142
	v_fmac_f32_e32 v141, v105, v143
	v_add_f32_e32 v147, v147, v141
	ds_read_b128 v[140:143], v75 offset:816
	s_waitcnt lgkmcnt(1)
	v_mul_f32_e32 v137, v95, v137
	v_fmac_f32_e32 v137, v72, v136
	v_fmac_f32_e32 v137, v96, v138
	v_fmac_f32_e32 v137, v101, v139
	v_add_f32_e32 v136, v147, v137
	s_waitcnt lgkmcnt(0)
	v_mul_f32_e32 v137, v97, v141
	v_fmac_f32_e32 v137, v73, v140
	v_fmac_f32_e32 v137, v99, v142
	v_fmac_f32_e32 v137, v98, v143
	v_add_f32_e32 v136, v136, v137
	v_mul_f32_e64 v137, |v136|, s3
	v_exp_f32_e32 v137, v137
	v_fmac_f32_e32 v146, 0x3377d1cf, v144
	v_fmac_f32_e32 v146, 0x3f317217, v144
	v_cmp_lt_f32_e64 s[16:17], |v144|, s46
	v_add_f32_e32 v137, 1.0, v137
	v_cndmask_b32_e32 v139, 0, v79, vcc
	v_cndmask_b32_e64 v138, v144, v146, s[16:17]
	v_cmp_gt_f32_e32 vcc, s44, v137
	v_sub_f32_e32 v138, v138, v139
	v_min_f32_e32 v146, 0, v136
	v_cndmask_b32_e64 v139, 0, 32, vcc
	v_ldexp_f32 v137, v137, v139
	v_log_f32_e32 v144, v137
	v_sub_f32_e32 v137, v145, v138
	v_fmamk_f32 v145, v137, 0x3d800000, v135
	ds_read_b128 v[136:139], v75 offset:832
	v_mul_f32_e32 v140, 0x3f317217, v144
	v_fma_f32 v147, v144, s45, -v140
	ds_read_b128 v[140:143], v75 offset:848
	v_fmac_f32_e32 v147, 0x3377d1cf, v144
	s_waitcnt lgkmcnt(1)
	v_mul_f32_e32 v137, v110, v137
	v_fmac_f32_e32 v137, v107, v136
	v_fmac_f32_e32 v137, v108, v138
	v_fmac_f32_e32 v137, v109, v139
	v_add_f32_e32 v148, v113, v137
	s_waitcnt lgkmcnt(0)
	v_mul_f32_e32 v141, v104, v141
	ds_read_b128 v[136:139], v75 offset:864
	v_fmac_f32_e32 v141, v103, v140
	v_fmac_f32_e32 v141, v100, v142
	v_fmac_f32_e32 v141, v105, v143
	v_add_f32_e32 v148, v148, v141
	ds_read_b128 v[140:143], v75 offset:880
	s_waitcnt lgkmcnt(1)
	v_mul_f32_e32 v137, v95, v137
	v_fmac_f32_e32 v137, v72, v136
	v_fmac_f32_e32 v137, v96, v138
	v_fmac_f32_e32 v137, v101, v139
	v_add_f32_e32 v136, v148, v137
	s_waitcnt lgkmcnt(0)
	v_mul_f32_e32 v137, v97, v141
	v_fmac_f32_e32 v137, v73, v140
	v_fmac_f32_e32 v137, v99, v142
	v_fmac_f32_e32 v137, v98, v143
	v_add_f32_e32 v136, v136, v137
	v_mul_f32_e64 v137, |v136|, s3
	v_exp_f32_e32 v137, v137
	v_fmac_f32_e32 v147, 0x3f317217, v144
	v_cmp_lt_f32_e64 s[16:17], |v144|, s46
	v_cndmask_b32_e32 v139, 0, v79, vcc
	v_add_f32_e32 v137, 1.0, v137
	v_cndmask_b32_e64 v138, v144, v147, s[16:17]
	v_cmp_gt_f32_e32 vcc, s44, v137
	v_sub_f32_e32 v138, v138, v139
	v_min_f32_e32 v147, 0, v136
	v_cndmask_b32_e64 v139, 0, 32, vcc
	v_ldexp_f32 v137, v137, v139
	v_log_f32_e32 v144, v137
	v_sub_f32_e32 v137, v146, v138
	v_fmamk_f32 v146, v137, 0x3d800000, v145
	ds_read_b128 v[136:139], v75 offset:896
	v_mul_f32_e32 v140, 0x3f317217, v144
	v_fma_f32 v148, v144, s45, -v140
	ds_read_b128 v[140:143], v75 offset:912
	v_fmac_f32_e32 v148, 0x3377d1cf, v144
	s_waitcnt lgkmcnt(1)
	v_mul_f32_e32 v137, v110, v137
	v_fmac_f32_e32 v137, v107, v136
	v_fmac_f32_e32 v137, v108, v138
	v_fmac_f32_e32 v137, v109, v139
	v_add_f32_e32 v149, v113, v137
	s_waitcnt lgkmcnt(0)
	v_mul_f32_e32 v141, v104, v141
	ds_read_b128 v[136:139], v75 offset:928
	v_fmac_f32_e32 v141, v103, v140
	v_fmac_f32_e32 v141, v100, v142
	v_fmac_f32_e32 v141, v105, v143
	v_add_f32_e32 v149, v149, v141
	ds_read_b128 v[140:143], v75 offset:944
	s_waitcnt lgkmcnt(1)
	v_mul_f32_e32 v137, v95, v137
	v_fmac_f32_e32 v137, v72, v136
	v_fmac_f32_e32 v137, v96, v138
	v_fmac_f32_e32 v137, v101, v139
	v_add_f32_e32 v136, v149, v137
	s_waitcnt lgkmcnt(0)
	v_mul_f32_e32 v137, v97, v141
	v_fmac_f32_e32 v137, v73, v140
	v_fmac_f32_e32 v137, v99, v142
	v_fmac_f32_e32 v137, v98, v143
	v_add_f32_e32 v136, v136, v137
	v_mul_f32_e64 v137, |v136|, s3
	v_exp_f32_e32 v137, v137
	v_fmac_f32_e32 v148, 0x3f317217, v144
	v_cmp_lt_f32_e64 s[16:17], |v144|, s46
	v_cndmask_b32_e32 v139, 0, v79, vcc
	v_add_f32_e32 v137, 1.0, v137
	v_cndmask_b32_e64 v138, v144, v148, s[16:17]
	v_cmp_gt_f32_e32 vcc, s44, v137
	v_sub_f32_e32 v138, v138, v139
	v_min_f32_e32 v148, 0, v136
	v_cndmask_b32_e64 v139, 0, 32, vcc
	v_ldexp_f32 v137, v137, v139
	v_log_f32_e32 v144, v137
	v_sub_f32_e32 v137, v147, v138
	v_fmamk_f32 v147, v137, 0x3d800000, v146
	ds_read_b128 v[136:139], v75 offset:960
	v_mul_f32_e32 v140, 0x3f317217, v144
	v_fma_f32 v149, v144, s45, -v140
	ds_read_b128 v[140:143], v75 offset:976
	v_fmac_f32_e32 v149, 0x3377d1cf, v144
	s_waitcnt lgkmcnt(1)
	v_mul_f32_e32 v110, v110, v137
	v_fmac_f32_e32 v110, v107, v136
	v_fmac_f32_e32 v110, v108, v138
	v_fmac_f32_e32 v110, v109, v139
	ds_read_b128 v[136:139], v75 offset:992
	s_waitcnt lgkmcnt(1)
	v_mul_f32_e32 v104, v104, v141
	v_fmac_f32_e32 v104, v103, v140
	v_fmac_f32_e32 v104, v100, v142
	v_fmac_f32_e32 v104, v105, v143
	ds_read_b128 v[140:143], v75 offset:1008
	s_waitcnt lgkmcnt(1)
	v_mul_f32_e32 v95, v95, v137
	v_fmac_f32_e32 v95, v72, v136
	v_add_f32_e32 v107, v113, v110
	v_fmac_f32_e32 v95, v96, v138
	v_add_f32_e32 v100, v107, v104
	v_fmac_f32_e32 v95, v101, v139
	v_add_f32_e32 v72, v100, v95
	s_waitcnt lgkmcnt(0)
	v_mul_f32_e32 v95, v97, v141
	v_fmac_f32_e32 v95, v73, v140
	v_fmac_f32_e32 v95, v99, v142
	v_fmac_f32_e32 v95, v98, v143
	v_add_f32_e32 v72, v72, v95
	v_mul_f32_e64 v73, |v72|, s3
	v_exp_f32_e32 v73, v73
	v_fmac_f32_e32 v149, 0x3f317217, v144
	v_cmp_lt_f32_e64 s[16:17], |v144|, s46
	v_cndmask_b32_e32 v96, 0, v79, vcc
	v_add_f32_e32 v73, 1.0, v73
	v_cndmask_b32_e64 v95, v144, v149, s[16:17]
	v_cmp_gt_f32_e32 vcc, s44, v73
	v_sub_f32_e32 v95, v95, v96
	v_sub_f32_e32 v95, v148, v95
	v_cndmask_b32_e64 v96, 0, 32, vcc
	v_ldexp_f32 v73, v73, v96
	v_log_f32_e32 v73, v73
	v_fmamk_f32 v98, v95, 0x3d800000, v147
	v_min_f32_e32 v72, 0, v72
	v_lshlrev_b32_e32 v94, 16, v94
	v_mul_f32_e32 v95, 0x3f317217, v73
	v_fma_f32 v95, v73, s45, -v95
	v_fmac_f32_e32 v95, 0x3377d1cf, v73
	v_fmac_f32_e32 v95, 0x3f317217, v73
	v_cmp_lt_f32_e64 s[16:17], |v73|, s46
	v_ashrrev_i32_e32 v69, 31, v68
	v_lshlrev_b64 v[68:69], 10, v[68:69]
	v_cndmask_b32_e64 v73, v73, v95, s[16:17]
	v_cndmask_b32_e32 v95, 0, v79, vcc
	v_sub_f32_e32 v73, v73, v95
	v_sub_f32_e32 v72, v72, v73
	v_fmamk_f32 v99, v72, 0x3d800000, v98
	ds_write_b32 v76, v99 offset:4096
	s_waitcnt lgkmcnt(0)
	s_barrier
	ds_read2st64_b32 v[72:73], v77 offset0:16 offset1:18
	ds_read2st64_b32 v[96:97], v77 offset0:20 offset1:22
	s_add_u32 s16, s28, s24
	s_addc_u32 s17, s29, 0
	v_ashrrev_i32_e32 v65, 31, v64
	s_waitcnt lgkmcnt(1)
	v_add_f32_e32 v72, 0, v72
	v_cndmask_b32_e64 v95, v72, 0, s[8:9]
	v_add_f32_e32 v72, v72, v73
	v_add_f32_e32 v73, v73, v95
	v_cndmask_b32_e64 v73, v95, v73, s[10:11]
	s_waitcnt lgkmcnt(0)
	v_add_f32_e32 v95, v96, v73
	v_add_f32_e32 v72, v72, v96
	v_cndmask_b32_e64 v73, v73, v95, s[12:13]
	v_add_f32_e32 v72, v72, v97
	v_add_f32_e32 v95, v97, v73
	v_cndmask_b32_e64 v96, v73, v95, s[14:15]
	v_mul_f32_e32 v72, 0x3fb8aa3b, v72
	v_exp_f32_e32 v95, v72
	v_add_f32_e32 v72, v125, v96
	v_mul_f32_e32 v72, 0x3fb8aa3b, v72
	v_exp_f32_e32 v97, v72
	v_lshl_add_u64 v[72:73], s[16:17], 0, v[2:3]
	v_lshl_add_u64 v[68:69], v[72:73], 0, v[68:69]
	v_lshlrev_b64 v[64:65], 10, v[64:65]
	v_rcp_f32_e32 v105, v97
	v_mul_f32_e32 v94, v97, v94
	v_cvt_pk_bf16_f32 v94, v94, s0
	ds_write_b16 v178, v94
	v_mul_f32_e32 v94, v105, v124
	v_cvt_pk_bf16_f32 v94, v94, s0
	ds_write_b16 v178, v94 offset:256
	v_add_f32_e32 v71, v126, v96
	v_mul_f32_e32 v71, 0x3fb8aa3b, v71
	v_exp_f32_e32 v71, v71
	v_mul_f32_e32 v70, v95, v105
	v_mul_f32_e32 v70, v70, v124
	v_cvt_pk_bf16_f32 v70, v70, s0
	ds_write_b16 v178, v70 offset:512
	v_rcp_f32_e32 v69, v71
	v_lshlrev_b32_e32 v68, 16, v93
	v_mul_f32_e32 v68, v71, v68
	v_cvt_pk_bf16_f32 v68, v68, s0
	ds_write_b16 v178, v68 offset:768
	v_mul_f32_e32 v68, v69, v123
	v_cvt_pk_bf16_f32 v68, v68, s0
	ds_write_b16 v178, v68 offset:1024
	v_add_f32_e32 v67, v127, v96
	v_mul_f32_e32 v67, 0x3fb8aa3b, v67
	v_exp_f32_e32 v67, v67
	v_mul_f32_e32 v66, v95, v69
	v_mul_f32_e32 v66, v66, v123
	v_cvt_pk_bf16_f32 v66, v66, s0
	v_lshl_add_u64 v[64:65], v[72:73], 0, v[64:65]
	ds_write_b16 v178, v66 offset:1280
	v_rcp_f32_e32 v65, v67
	v_lshlrev_b32_e32 v64, 16, v92
	v_mul_f32_e32 v64, v67, v64
	v_cvt_pk_bf16_f32 v64, v64, s0
	ds_write_b16 v178, v64 offset:1536
	v_mul_f32_e32 v64, v65, v122
	v_cvt_pk_bf16_f32 v64, v64, s0
	ds_write_b16 v178, v64 offset:1792
	v_add_f32_e32 v63, v128, v96
	v_mul_f32_e32 v63, 0x3fb8aa3b, v63
	v_exp_f32_e32 v63, v63
	v_ashrrev_i32_e32 v61, 31, v60
	v_mul_f32_e32 v62, v95, v65
	v_mul_f32_e32 v62, v62, v122
	v_lshlrev_b64 v[60:61], 10, v[60:61]
	v_cvt_pk_bf16_f32 v62, v62, s0
	v_lshl_add_u64 v[60:61], v[72:73], 0, v[60:61]
	ds_write_b16 v178, v62 offset:2048
	v_rcp_f32_e32 v61, v63
	v_lshlrev_b32_e32 v60, 16, v90
	v_mul_f32_e32 v60, v63, v60
	v_cvt_pk_bf16_f32 v60, v60, s0
	ds_write_b16 v178, v60 offset:2304
	v_mul_f32_e32 v60, v61, v117
	v_cvt_pk_bf16_f32 v60, v60, s0
	ds_write_b16 v178, v60 offset:2560
	v_add_f32_e32 v59, v129, v96
	v_mul_f32_e32 v59, 0x3fb8aa3b, v59
	v_exp_f32_e32 v59, v59
	v_ashrrev_i32_e32 v57, 31, v56
	v_mul_f32_e32 v58, v95, v61
	v_mul_f32_e32 v58, v58, v117
	v_lshlrev_b64 v[56:57], 10, v[56:57]
	v_cvt_pk_bf16_f32 v58, v58, s0
	v_lshl_add_u64 v[56:57], v[72:73], 0, v[56:57]
	ds_write_b16 v178, v58 offset:2816
	v_rcp_f32_e32 v57, v59
	v_lshlrev_b32_e32 v56, 16, v91
	v_mul_f32_e32 v56, v59, v56
	v_lshlrev_b32_e32 v116, 16, v116
	v_cvt_pk_bf16_f32 v56, v56, s0
	ds_write_b16 v178, v56 offset:3072
	v_mul_f32_e32 v56, v57, v116
	v_cvt_pk_bf16_f32 v56, v56, s0
	ds_write_b16 v178, v56 offset:3328
	v_add_f32_e32 v55, v130, v96
	v_mul_f32_e32 v55, 0x3fb8aa3b, v55
	v_exp_f32_e32 v55, v55
	v_ashrrev_i32_e32 v53, 31, v52
	v_mul_f32_e32 v54, v95, v57
	v_mul_f32_e32 v54, v54, v116
	v_lshlrev_b64 v[52:53], 10, v[52:53]
	v_cvt_pk_bf16_f32 v54, v54, s0
	v_lshl_add_u64 v[52:53], v[72:73], 0, v[52:53]
	ds_write_b16 v178, v54 offset:3584
	v_rcp_f32_e32 v53, v55
	v_lshlrev_b32_e32 v52, 16, v89
	v_mul_f32_e32 v52, v55, v52
	v_cvt_pk_bf16_f32 v52, v52, s0
	ds_write_b16 v178, v52 offset:3840
	v_mul_f32_e32 v52, v53, v114
	v_cvt_pk_bf16_f32 v52, v52, s0
	ds_write_b16 v178, v52 offset:4096
	v_add_f32_e32 v51, v131, v96
	v_mul_f32_e32 v51, 0x3fb8aa3b, v51
	v_exp_f32_e32 v51, v51
	v_ashrrev_i32_e32 v49, 31, v48
	v_mul_f32_e32 v50, v95, v53
	v_mul_f32_e32 v50, v50, v114
	v_lshlrev_b64 v[48:49], 10, v[48:49]
	v_cvt_pk_bf16_f32 v50, v50, s0
	v_lshl_add_u64 v[48:49], v[72:73], 0, v[48:49]
	ds_write_b16 v178, v50 offset:4352
	v_rcp_f32_e32 v49, v51
	v_lshlrev_b32_e32 v48, 16, v88
	v_mul_f32_e32 v48, v51, v48
	v_cvt_pk_bf16_f32 v48, v48, s0
	ds_write_b16 v178, v48 offset:4608
	v_mul_f32_e32 v48, v49, v111
	v_cvt_pk_bf16_f32 v48, v48, s0
	ds_write_b16 v178, v48 offset:4864
	v_add_f32_e32 v47, v132, v96
	v_mul_f32_e32 v47, 0x3fb8aa3b, v47
	v_exp_f32_e32 v47, v47
	v_ashrrev_i32_e32 v45, 31, v44
	v_mul_f32_e32 v46, v95, v49
	v_mul_f32_e32 v46, v46, v111
	v_lshlrev_b64 v[44:45], 10, v[44:45]
	v_cvt_pk_bf16_f32 v46, v46, s0
	v_lshl_add_u64 v[44:45], v[72:73], 0, v[44:45]
	ds_write_b16 v178, v46 offset:5120
	v_rcp_f32_e32 v45, v47
	v_lshlrev_b32_e32 v44, 16, v86
	v_mul_f32_e32 v44, v47, v44
	v_cvt_pk_bf16_f32 v44, v44, s0
	ds_write_b16 v178, v44 offset:5376
	v_mul_f32_e32 v44, v45, v115
	v_cvt_pk_bf16_f32 v44, v44, s0
	ds_write_b16 v178, v44 offset:5632
	v_add_f32_e32 v43, v133, v96
	v_mul_f32_e32 v43, 0x3fb8aa3b, v43
	v_exp_f32_e32 v43, v43
	v_ashrrev_i32_e32 v41, 31, v40
	v_mul_f32_e32 v42, v95, v45
	v_mul_f32_e32 v42, v42, v115
	v_lshlrev_b64 v[40:41], 10, v[40:41]
	v_cvt_pk_bf16_f32 v42, v42, s0
	v_lshl_add_u64 v[40:41], v[72:73], 0, v[40:41]
	ds_write_b16 v178, v42 offset:5888
	v_rcp_f32_e32 v41, v43
	v_lshlrev_b32_e32 v40, 16, v87
	v_mul_f32_e32 v40, v43, v40
	v_lshlrev_b32_e32 v112, 16, v112
	v_cvt_pk_bf16_f32 v40, v40, s0
	ds_write_b16 v178, v40 offset:6144
	v_mul_f32_e32 v40, v41, v112
	v_cvt_pk_bf16_f32 v40, v40, s0
	ds_write_b16 v178, v40 offset:6400
	v_add_f32_e32 v39, v134, v96
	v_mul_f32_e32 v39, 0x3fb8aa3b, v39
	v_exp_f32_e32 v39, v39
	v_ashrrev_i32_e32 v37, 31, v36
	v_mul_f32_e32 v38, v95, v41
	v_mul_f32_e32 v38, v38, v112
	v_lshlrev_b64 v[36:37], 10, v[36:37]
	v_cvt_pk_bf16_f32 v38, v38, s0
	v_lshl_add_u64 v[36:37], v[72:73], 0, v[36:37]
	ds_write_b16 v178, v38 offset:6656
	v_rcp_f32_e32 v37, v39
	v_lshlrev_b32_e32 v36, 16, v85
	v_mul_f32_e32 v36, v39, v36
	v_cvt_pk_bf16_f32 v36, v36, s0
	ds_write_b16 v178, v36 offset:6912
	v_mul_f32_e32 v36, v37, v106
	v_cvt_pk_bf16_f32 v36, v36, s0
	ds_write_b16 v178, v36 offset:7168
	v_add_f32_e32 v35, v135, v96
	v_mul_f32_e32 v35, 0x3fb8aa3b, v35
	v_exp_f32_e32 v35, v35
	v_ashrrev_i32_e32 v33, 31, v32
	v_mul_f32_e32 v34, v95, v37
	v_mul_f32_e32 v34, v34, v106
	v_lshlrev_b64 v[32:33], 10, v[32:33]
	v_cvt_pk_bf16_f32 v34, v34, s0
	v_lshl_add_u64 v[32:33], v[72:73], 0, v[32:33]
	ds_write_b16 v178, v34 offset:7424
	v_rcp_f32_e32 v33, v35
	v_lshlrev_b32_e32 v32, 16, v84
	v_mul_f32_e32 v32, v35, v32
	v_cvt_pk_bf16_f32 v32, v32, s0
	ds_write_b16 v178, v32 offset:7680
	v_mul_f32_e32 v32, v33, v102
	v_cvt_pk_bf16_f32 v32, v32, s0
	ds_write_b16 v178, v32 offset:7936
	v_add_f32_e32 v31, v145, v96
	v_mul_f32_e32 v31, 0x3fb8aa3b, v31
	v_exp_f32_e32 v31, v31
	v_ashrrev_i32_e32 v29, 31, v28
	v_mul_f32_e32 v30, v95, v33
	v_mul_f32_e32 v30, v30, v102
	v_lshlrev_b64 v[28:29], 10, v[28:29]
	v_cvt_pk_bf16_f32 v30, v30, s0
	v_lshl_add_u64 v[28:29], v[72:73], 0, v[28:29]
	ds_write_b16 v178, v30 offset:8192
	v_rcp_f32_e32 v29, v31
	v_lshlrev_b32_e32 v28, 16, v82
	v_mul_f32_e32 v28, v31, v28
	v_cvt_pk_bf16_f32 v28, v28, s0
	ds_write_b16 v178, v28 offset:8448
	v_mul_f32_e32 v28, v29, v5
	v_cvt_pk_bf16_f32 v28, v28, s0
	ds_write_b16 v178, v28 offset:8704
	v_mul_f32_e32 v26, v95, v29
	v_mul_f32_e32 v5, v26, v5
	v_add_f32_e32 v26, v146, v96
	v_mul_f32_e32 v26, 0x3fb8aa3b, v26
	v_exp_f32_e32 v26, v26
	v_ashrrev_i32_e32 v25, 31, v24
	v_lshlrev_b64 v[24:25], 10, v[24:25]
	v_cvt_pk_bf16_f32 v5, v5, s0
	v_lshl_add_u64 v[24:25], v[72:73], 0, v[24:25]
	ds_write_b16 v178, v5 offset:8960
	v_rcp_f32_e32 v24, v26
	s_waitcnt vmcnt(43)
	v_lshlrev_b32_e32 v5, 16, v83
	v_mul_f32_e32 v5, v26, v5
	s_waitcnt vmcnt(42)
	v_lshlrev_b32_e32 v100, 16, v118
	v_cvt_pk_bf16_f32 v5, v5, s0
	ds_write_b16 v178, v5 offset:9216
	v_mul_f32_e32 v5, v24, v100
	v_cvt_pk_bf16_f32 v5, v5, s0
	ds_write_b16 v178, v5 offset:9472
	v_add_f32_e32 v22, v147, v96
	v_mul_f32_e32 v22, 0x3fb8aa3b, v22
	v_exp_f32_e32 v22, v22
	v_ashrrev_i32_e32 v21, 31, v20
	v_mul_f32_e32 v5, v95, v24
	v_mul_f32_e32 v5, v5, v100
	v_lshlrev_b64 v[20:21], 10, v[20:21]
	v_cvt_pk_bf16_f32 v5, v5, s0
	v_lshl_add_u64 v[20:21], v[72:73], 0, v[20:21]
	ds_write_b16 v178, v5 offset:9728
	v_rcp_f32_e32 v20, v22
	s_waitcnt vmcnt(44)
	v_lshlrev_b32_e32 v5, 16, v81
	v_mul_f32_e32 v5, v22, v5
	s_waitcnt vmcnt(43)
	v_lshlrev_b32_e32 v101, 16, v119
	v_cvt_pk_bf16_f32 v5, v5, s0
	ds_write_b16 v178, v5 offset:9984
	v_mul_f32_e32 v5, v20, v101
	v_cvt_pk_bf16_f32 v5, v5, s0
	ds_write_b16 v178, v5 offset:10240
	v_add_f32_e32 v18, v98, v96
	v_mul_f32_e32 v18, 0x3fb8aa3b, v18
	v_exp_f32_e32 v18, v18
	v_ashrrev_i32_e32 v17, 31, v16
	v_mul_f32_e32 v5, v95, v20
	v_mul_f32_e32 v5, v5, v101
	v_lshlrev_b64 v[16:17], 10, v[16:17]
	v_cvt_pk_bf16_f32 v5, v5, s0
	v_lshl_add_u64 v[16:17], v[72:73], 0, v[16:17]
	ds_write_b16 v178, v5 offset:10496
	v_rcp_f32_e32 v16, v18
	s_waitcnt vmcnt(45)
	v_lshlrev_b32_e32 v5, 16, v80
	v_mul_f32_e32 v5, v18, v5
	s_waitcnt vmcnt(44)
	v_lshlrev_b32_e32 v103, 16, v120
	v_cvt_pk_bf16_f32 v5, v5, s0
	ds_write_b16 v178, v5 offset:10752
	v_mul_f32_e32 v5, v16, v103
	v_cvt_pk_bf16_f32 v5, v5, s0
	ds_write_b16 v178, v5 offset:11008
	v_add_f32_e32 v14, v96, v99
	v_mul_f32_e32 v14, 0x3fb8aa3b, v14
	v_exp_f32_e32 v14, v14
	v_ashrrev_i32_e32 v13, 31, v12
	v_mul_f32_e32 v5, v95, v16
	v_mul_f32_e32 v5, v5, v103
	v_lshlrev_b64 v[12:13], 10, v[12:13]
	v_cvt_pk_bf16_f32 v5, v5, s0
	v_lshl_add_u64 v[12:13], v[72:73], 0, v[12:13]
	ds_write_b16 v178, v5 offset:11264
	s_waitcnt vmcnt(46)
	v_lshlrev_b32_e32 v5, 16, v7
	v_rcp_f32_e32 v7, v14
	v_mul_f32_e32 v5, v14, v5
	s_waitcnt vmcnt(45)
	v_lshlrev_b32_e32 v104, 16, v121
	v_cvt_pk_bf16_f32 v5, v5, s0
	ds_write_b16 v178, v5 offset:11520
	v_mul_f32_e32 v5, v7, v104
	v_cvt_pk_bf16_f32 v5, v5, s0
	v_ashrrev_i32_e32 v9, 31, v8
	ds_write_b16 v178, v5 offset:11776
	v_mul_f32_e32 v5, v95, v7
	v_mul_f32_e32 v5, v5, v104
	v_lshlrev_b64 v[8:9], 10, v[8:9]
	v_cvt_pk_bf16_f32 v5, v5, s0
	v_lshl_add_u64 v[8:9], v[72:73], 0, v[8:9]
	ds_write_b16 v178, v5 offset:12032
	s_waitcnt lgkmcnt(0)
	s_barrier
	v_mov_b64_e32 v[194:195], s[94:95]
	v_mov_b64_e32 v[196:197], s[96:97]
	s_mov_b32 s100, 0x5555556
	v_mov_b32_e32 v207, 0
	v_mov_b32_e32 v188, v192
	v_mul_hi_u32 v189, v188, s100
	v_mul_u32_u24_e32 v190, 48, v189
	v_sub_u32_e32 v190, v188, v190
	ds_read_b128 v[184:187], v177
	v_and_b32_e32 v202, 15, v190
	v_lshlrev_b32_e32 v202, 4, v202
	v_bfe_u32 v203, v190, 4, 1
	v_lshl_add_u32 v202, v203, 10, v202
	v_mad_u32_u24 v204, v189, s99, v202
	v_lshlrev_b32_e32 v205, 10, v189
	v_lshl_add_u32 v205, v190, 4, v205
	v_add_u32_e32 v205, 0xfffffe00, v205
	v_cmp_gt_u32_e32 vcc, 32, v190
	s_nop 1
	v_cndmask_b32_e32 v206, v205, v204, vcc
	v_cndmask_b32_e32 v200, v196, v194, vcc
	v_cndmask_b32_e32 v201, v197, v195, vcc
	v_lshl_add_u64 v[200:201], v[206:207], 0, v[200:201]
	s_waitcnt lgkmcnt(0)
	global_store_dwordx4 v[200:201], v[184:187], off
	v_add_u32_e32 v188, 0x200, v192
	v_mul_hi_u32 v189, v188, s100
	v_mul_u32_u24_e32 v190, 48, v189
	v_sub_u32_e32 v190, v188, v190
	ds_read_b128 v[208:211], v177 offset:8192
	v_and_b32_e32 v202, 15, v190
	v_lshlrev_b32_e32 v202, 4, v202
	v_bfe_u32 v203, v190, 4, 1
	v_lshl_add_u32 v202, v203, 10, v202
	v_mad_u32_u24 v204, v189, s99, v202
	v_lshlrev_b32_e32 v205, 10, v189
	v_lshl_add_u32 v205, v190, 4, v205
	v_add_u32_e32 v205, 0xfffffe00, v205
	v_cmp_gt_u32_e32 vcc, 32, v190
	s_nop 1
	v_cndmask_b32_e32 v206, v205, v204, vcc
	v_cndmask_b32_e32 v200, v196, v194, vcc
	v_cndmask_b32_e32 v201, v197, v195, vcc
	v_lshl_add_u64 v[200:201], v[206:207], 0, v[200:201]
	s_waitcnt lgkmcnt(0)
	global_store_dwordx4 v[200:201], v[208:211], off
	v_add_u32_e32 v188, 0x400, v192
	v_mul_hi_u32 v189, v188, s100
	v_mul_u32_u24_e32 v190, 48, v189
	v_sub_u32_e32 v190, v188, v190
	ds_read_b128 v[184:187], v177 offset:16384
	v_and_b32_e32 v202, 15, v190
	v_lshlrev_b32_e32 v202, 4, v202
	v_bfe_u32 v203, v190, 4, 1
	v_lshl_add_u32 v202, v203, 10, v202
	v_mad_u32_u24 v204, v189, s99, v202
	v_lshlrev_b32_e32 v205, 10, v189
	v_lshl_add_u32 v205, v190, 4, v205
	v_add_u32_e32 v205, 0xfffffe00, v205
	v_cmp_gt_u32_e32 vcc, 32, v190
	s_nop 1
	v_cndmask_b32_e32 v206, v205, v204, vcc
	v_cndmask_b32_e32 v200, v196, v194, vcc
	v_cndmask_b32_e32 v201, v197, v195, vcc
	v_lshl_add_u64 v[200:201], v[206:207], 0, v[200:201]
	s_waitcnt lgkmcnt(0)
	global_store_dwordx4 v[200:201], v[184:187], off
	v_add_u32_e32 v188, 0x600, v192
	v_mul_hi_u32 v189, v188, s100
	v_mul_u32_u24_e32 v190, 48, v189
	v_sub_u32_e32 v190, v188, v190
	ds_read_b128 v[208:211], v177 offset:24576
	v_and_b32_e32 v202, 15, v190
	v_lshlrev_b32_e32 v202, 4, v202
	v_bfe_u32 v203, v190, 4, 1
	v_lshl_add_u32 v202, v203, 10, v202
	v_mad_u32_u24 v204, v189, s99, v202
	v_lshlrev_b32_e32 v205, 10, v189
	v_lshl_add_u32 v205, v190, 4, v205
	v_add_u32_e32 v205, 0xfffffe00, v205
	v_cmp_gt_u32_e32 vcc, 32, v190
	s_nop 1
	v_cndmask_b32_e32 v206, v205, v204, vcc
	v_cndmask_b32_e32 v200, v196, v194, vcc
	v_cndmask_b32_e32 v201, v197, v195, vcc
	v_lshl_add_u64 v[200:201], v[206:207], 0, v[200:201]
	s_waitcnt lgkmcnt(0)
	global_store_dwordx4 v[200:201], v[208:211], off
	v_add_u32_e32 v188, 0x800, v192
	v_mul_hi_u32 v189, v188, s100
	v_mul_u32_u24_e32 v190, 48, v189
	v_sub_u32_e32 v190, v188, v190
	ds_read_b128 v[184:187], v177 offset:32768
	v_and_b32_e32 v202, 15, v190
	v_lshlrev_b32_e32 v202, 4, v202
	v_bfe_u32 v203, v190, 4, 1
	v_lshl_add_u32 v202, v203, 10, v202
	v_mad_u32_u24 v204, v189, s99, v202
	v_lshlrev_b32_e32 v205, 10, v189
	v_lshl_add_u32 v205, v190, 4, v205
	v_add_u32_e32 v205, 0xfffffe00, v205
	v_cmp_gt_u32_e32 vcc, 32, v190
	s_nop 1
	v_cndmask_b32_e32 v206, v205, v204, vcc
	v_cndmask_b32_e32 v200, v196, v194, vcc
	v_cndmask_b32_e32 v201, v197, v195, vcc
	v_lshl_add_u64 v[200:201], v[206:207], 0, v[200:201]
	s_waitcnt lgkmcnt(0)
	global_store_dwordx4 v[200:201], v[184:187], off
	v_add_u32_e32 v188, 0xa00, v192
	v_mul_hi_u32 v189, v188, s100
	v_mul_u32_u24_e32 v190, 48, v189
	v_sub_u32_e32 v190, v188, v190
	ds_read_b128 v[208:211], v177 offset:40960
	v_and_b32_e32 v202, 15, v190
	v_lshlrev_b32_e32 v202, 4, v202
	v_bfe_u32 v203, v190, 4, 1
	v_lshl_add_u32 v202, v203, 10, v202
	v_mad_u32_u24 v204, v189, s99, v202
	v_lshlrev_b32_e32 v205, 10, v189
	v_lshl_add_u32 v205, v190, 4, v205
	v_add_u32_e32 v205, 0xfffffe00, v205
	v_cmp_gt_u32_e32 vcc, 32, v190
	s_nop 1
	v_cndmask_b32_e32 v206, v205, v204, vcc
	v_cndmask_b32_e32 v200, v196, v194, vcc
	v_cndmask_b32_e32 v201, v197, v195, vcc
	v_lshl_add_u64 v[200:201], v[206:207], 0, v[200:201]
	s_waitcnt lgkmcnt(0)
	global_store_dwordx4 v[200:201], v[208:211], off
	s_and_saveexec_b64 s[16:17], s[8:9]
	s_cbranch_execz .LBB0_472
	s_lshl_b32 s24, s51, 6
	s_or_b32 s28, s24, s50
	s_ashr_i32 s29, s28, 31
	s_lshl_b64 s[28:29], s[28:29], 11
	s_add_u32 s24, s26, s28
	s_addc_u32 s27, s27, s29
	s_lshl_b32 s26, s49, 2
	s_add_u32 s26, s24, s26
	s_addc_u32 s27, s27, 0
	v_mov_b32_e32 v7, v3
	v_lshl_add_u64 v[8:9], s[26:27], 0, v[6:7]
	v_add_co_u32_e32 v8, vcc, 0x2000000, v8
	s_nop 1
	v_addc_co_u32_e32 v9, vcc, 0, v9, vcc
	global_store_dword v[8:9], v95, off
	s_branch .LBB0_472
